# G1 rope table loads: flat_load -> global_load (64 sites)
# baseline (speedup 1.0000x reference)
; __device__ __forceinline__ unsigned cvt_pk_bf16(float lo, float hi) { unsigned r; asm volatile("v_cvt_pk_bf16_f32 %0, %1, %2" : "=v"(r) : "v"(lo), "v"(hi)); return r; }
;     __device__ __forceinline__ void operator()(const pg8::f32x4 (&acc)[2][2][4][2], const pg8::Unit& u, int wr, int wc, int fr, int fq) const {
;     ...
;                     const int i0 = 8 * (fq & 1); const bool odd = (wc & 1) != 0; const float sgn = (fq < 2) ? -1.f : 1.f;
; #pragma unroll
;                     for (int ai = 0; ai < 2; ++ai)
; #pragma unroll
;                         for (int m = 0; m < 4; ++m) { const int s = sbase + ai * HALF + m * 16;
;                             f32x4 v0 = acc[ai][bj][m][0], v1 = acc[ai][bj][m][1];
;                             if (!isctx) {
;                                 const int pos = odd ? (s & 63) : (s >> 6);
;                                 const f32x4 c0 = *(const f32x4*)(ropeC + pos * 16 + i0), c1 = *(const f32x4*)(ropeC + pos * 16 + i0 + 4);
;                                 const f32x4 s0 = *(const f32x4*)(ropeS + pos * 16 + i0), s1 = *(const f32x4*)(ropeS + pos * 16 + i0 + 4);
; #pragma unroll
;                                 for (int j = 0; j < 4; ++j) { const float p0 = __shfl_xor(v0[j], 32), p1 = __shfl_xor(v1[j], 32);
;                                     v0[j] = v0[j] * c0[j] + sgn * p0 * s0[j]; v1[j] = v1[j] * c1[j] + sgn * p1 * s1[j]; }
;                             }
;                             if (pn < 2) { v0 = v0 * QSCALE; v1 = v1 * QSCALE; }
;                             u32x4 w; w.x = cvt_pk_bf16(v0[0], v0[1]); w.y = cvt_pk_bf16(v0[2], v0[3]); w.z = cvt_pk_bf16(v1[0], v1[1]); w.w = cvt_pk_bf16(v1[2], v1[3]);
;                             const size_t grow = grow0 + ai * HALF + m * 16;
;                             if (pn < 2) *(u32x4*)(QB + grow * 512 + pn * 256 + bj * HALF + c8) = w; else *(u32x4*)(KB + grow * 128 + c8) = w; asm volatile("" ::: "memory"); }
.LBB0_190:
	s_and_b64 vcc, exec, s[6:7]
	s_cbranch_vccz .LBB0_235
	v_and_b32_e32 v143, 8, v200
	v_lshlrev_b32_e32 v176, 2, v143
	v_lshl_add_u64 v[152:153], s[0:1], 0, v[176:177]
	s_mov_b64 s[6:7], 0x2d50000
	v_cmp_gt_i32_e32 vcc, 2, v199
	v_lshl_add_u64 v[154:155], v[152:153], 0, s[6:7]
	s_mov_b64 s[6:7], 0x2d52000
	v_cndmask_b32_e64 v143, 0, 1, s[8:9]
	v_cndmask_b32_e64 v150, 1.0, -1.0, vcc
	v_lshl_add_u64 v[152:153], v[152:153], 0, s[6:7]
	v_cmp_ne_u32_e64 s[6:7], 1, v143
	s_andn2_b64 vcc, exec, s[8:9]
	v_and_b32_e32 v149, 63, v148
	s_cbranch_vccnz .LBB0_193
	v_ashrrev_i32_e32 v143, 6, v144
	v_cndmask_b32_e64 v143, v149, v143, s[10:11]
	v_lshlrev_b32_e32 v156, 4, v143
	v_ashrrev_i32_e32 v157, 31, v156
	v_lshlrev_b64 v[164:165], 2, v[156:157]
	v_lshl_add_u64 v[160:161], v[154:155], 0, v[164:165]
	global_load_dwordx4 v[156:159], v[160:161], off
	s_nop 0
	global_load_dwordx4 v[160:163], v[160:161], off offset:16
	v_lshl_add_u64 v[168:169], v[152:153], 0, v[164:165]
	global_load_dwordx4 v[164:167], v[168:169], off
	s_nop 0
	global_load_dwordx4 v[168:171], v[168:169], off offset:16
	v_and_b32_e32 v145, 64, v232
	v_xor_b32_e32 v143, 32, v232
	v_add_u32_e32 v145, 64, v145
	v_cmp_lt_i32_e32 vcc, v143, v145
	s_nop 1
	v_cndmask_b32_e32 v143, v232, v143, vcc
	v_lshlrev_b32_e32 v143, 2, v143
	ds_bpermute_b32 v172, v143, v120
	ds_bpermute_b32 v174, v143, v124
	ds_bpermute_b32 v173, v143, v121
	ds_bpermute_b32 v175, v143, v125
	ds_bpermute_b32 v145, v143, v122
	s_waitcnt lgkmcnt(0)
	v_mul_f32_e32 v145, v150, v145
	s_waitcnt vmcnt(0)
	v_pk_mul_f32 v[120:121], v[120:121], v[156:157]
	v_pk_mul_f32 v[156:157], v[150:151], v[172:173] op_sel_hi:[0,1]
	v_pk_mul_f32 v[124:125], v[124:125], v[160:161]
	v_pk_mul_f32 v[160:161], v[150:151], v[174:175] op_sel_hi:[0,1]
	ds_bpermute_b32 v151, v143, v126
	v_mul_f32_e32 v122, v122, v158
	v_mul_f32_e32 v158, v166, v145
	v_mul_f32_e32 v126, v126, v162
	v_mov_b32_e32 v166, v123
	s_waitcnt lgkmcnt(0)
	v_mul_f32_e32 v145, v150, v151
	v_mul_f32_e32 v162, v170, v145
	ds_bpermute_b32 v145, v143, v123
	ds_bpermute_b32 v143, v143, v127
	v_mov_b32_e32 v172, v159
	v_pk_fma_f32 v[120:121], v[164:165], v[156:157], v[120:121]
	v_mov_b32_e32 v170, v127
	s_waitcnt lgkmcnt(1)
	v_mul_f32_e32 v173, v150, v145
	s_waitcnt lgkmcnt(0)
	v_mul_f32_e32 v157, v150, v143
	v_mov_b32_e32 v156, v163
	v_pk_mul_f32 v[166:167], v[166:167], v[172:173]
	v_pk_mul_f32 v[156:157], v[170:171], v[156:157]
	v_mov_b32_e32 v123, v166
	v_mov_b32_e32 v159, v167
	v_mov_b32_e32 v127, v156
	v_mov_b32_e32 v163, v157
	v_pk_add_f32 v[122:123], v[122:123], v[158:159]
	v_pk_fma_f32 v[124:125], v[168:169], v[160:161], v[124:125]
	v_pk_add_f32 v[126:127], v[126:127], v[162:163]
.LBB0_193:
	s_cmp_lg_u32 s91, 2
	s_cselect_b64 s[70:71], -1, 0
	s_lshl_b32 s8, s91, 8
	s_ashr_i32 s9, s8, 31
	s_lshl_b64 s[8:9], s[8:9], 1
	s_add_u32 s8, s0, s8
	v_ashrrev_i32_e32 v143, 31, v142
	s_addc_u32 s9, s1, s9
	v_lshlrev_b64 v[158:159], 1, v[142:143]
	v_lshl_add_u64 v[156:157], s[8:9], 0, v[158:159]
	s_mov_b64 s[8:9], 0x1bc00000
	s_cmp_eq_u32 s91, 2
	v_lshl_add_u64 v[156:157], v[156:157], 0, s[8:9]
	v_lshl_add_u64 v[158:159], s[0:1], 0, v[158:159]
	s_mov_b64 s[8:9], 0x1fe00000
	v_lshl_add_u64 v[158:159], v[158:159], 0, s[8:9]
	s_cselect_b64 s[8:9], -1, 0
	v_pk_mul_f32 v[160:161], v[122:123], s[48:49] op_sel_hi:[1,0]
	v_pk_mul_f32 v[162:163], v[120:121], s[48:49] op_sel_hi:[1,0]
	v_pk_mul_f32 v[164:165], v[126:127], s[48:49] op_sel_hi:[1,0]
	v_pk_mul_f32 v[166:167], v[124:125], s[48:49] op_sel_hi:[1,0]
	s_and_b64 s[18:19], s[8:9], exec
	v_cndmask_b32_e64 v126, v164, v126, s[8:9]
	v_cndmask_b32_e64 v127, v165, v127, s[8:9]
	v_cndmask_b32_e64 v124, v166, v124, s[8:9]
	v_cndmask_b32_e64 v125, v167, v125, s[8:9]
	v_cndmask_b32_e64 v123, v161, v123, s[8:9]
	v_cndmask_b32_e64 v120, v162, v120, s[8:9]
	v_cndmask_b32_e64 v121, v163, v121, s[8:9]
	s_cselect_b32 s18, 8, 10
	v_cndmask_b32_e64 v151, v160, v122, s[8:9]
	v_cvt_pk_bf16_f32 v122, v120, v121
	v_cvt_pk_bf16_f32 v123, v151, v123
	v_cvt_pk_bf16_f32 v124, v124, v125
	v_cvt_pk_bf16_f32 v125, v126, v127
	v_cndmask_b32_e64 v121, v157, v159, s[8:9]
	v_cndmask_b32_e64 v120, v156, v158, s[8:9]
	v_lshlrev_b64 v[126:127], s18, v[146:147]
	v_lshl_add_u64 v[126:127], v[120:121], 0, v[126:127]
	global_store_dwordx4 v[126:127], v[122:125], off
	v_add_u32_e32 v145, 16, v148
	v_and_b32_e32 v145, 63, v145
	s_and_b64 vcc, exec, s[6:7]
	s_cbranch_vccnz .LBB0_195
	v_add_u32_e32 v122, 16, v144
	v_ashrrev_i32_e32 v122, 6, v122
	v_cndmask_b32_e64 v122, v145, v122, s[10:11]
	v_lshlrev_b32_e32 v122, 4, v122
	v_ashrrev_i32_e32 v123, 31, v122
	v_lshlrev_b64 v[126:127], 2, v[122:123]
	v_lshl_add_u64 v[158:159], v[154:155], 0, v[126:127]
	global_load_dwordx4 v[122:125], v[158:159], off
	s_nop 0
	global_load_dwordx4 v[158:161], v[158:159], off offset:16
	v_lshl_add_u64 v[126:127], v[152:153], 0, v[126:127]
	global_load_dwordx4 v[162:165], v[126:127], off
	global_load_dwordx4 v[166:169], v[126:127], off offset:16
	v_and_b32_e32 v127, 64, v232
	v_xor_b32_e32 v126, 32, v232
	v_add_u32_e32 v127, 64, v127
	v_cmp_lt_i32_e32 vcc, v126, v127
	s_nop 1
	v_cndmask_b32_e32 v126, v232, v126, vcc
	v_lshlrev_b32_e32 v151, 2, v126
	ds_bpermute_b32 v126, v151, v112
	ds_bpermute_b32 v170, v151, v116
	ds_bpermute_b32 v127, v151, v113
	ds_bpermute_b32 v171, v151, v117
	s_waitcnt vmcnt(0) lgkmcnt(0)
	v_pk_mul_f32 v[112:113], v[112:113], v[122:123]
	v_pk_mul_f32 v[116:117], v[116:117], v[158:159]
	ds_bpermute_b32 v158, v151, v114
	ds_bpermute_b32 v159, v151, v118
	v_pk_mul_f32 v[122:123], v[150:151], v[126:127] op_sel_hi:[0,1]
	v_pk_mul_f32 v[126:127], v[150:151], v[170:171] op_sel_hi:[0,1]
	v_mul_f32_e32 v114, v114, v124
	s_waitcnt lgkmcnt(1)
	v_mul_f32_e32 v124, v150, v158
	s_waitcnt lgkmcnt(0)
	v_mul_f32_e32 v158, v150, v159
	ds_bpermute_b32 v159, v151, v115
	ds_bpermute_b32 v151, v151, v119
	v_mul_f32_e32 v124, v164, v124
	v_mul_f32_e32 v158, v168, v158
	v_mov_b32_e32 v164, v115
	s_waitcnt lgkmcnt(1)
	v_mul_f32_e32 v171, v150, v159
	v_mov_b32_e32 v170, v125
	v_pk_fma_f32 v[112:113], v[162:163], v[122:123], v[112:113]
	s_waitcnt lgkmcnt(0)
	v_mul_f32_e32 v123, v150, v151
	v_mov_b32_e32 v168, v119
	v_mov_b32_e32 v122, v161
	v_pk_mul_f32 v[164:165], v[164:165], v[170:171]
	v_pk_mul_f32 v[122:123], v[168:169], v[122:123]
	v_mul_f32_e32 v118, v118, v160
	v_mov_b32_e32 v115, v164
	v_mov_b32_e32 v125, v165
	v_mov_b32_e32 v119, v122
	v_mov_b32_e32 v159, v123
	v_pk_add_f32 v[114:115], v[114:115], v[124:125]
	v_pk_fma_f32 v[116:117], v[166:167], v[126:127], v[116:117]
	v_pk_add_f32 v[118:119], v[118:119], v[158:159]
; __device__ __forceinline__ unsigned cvt_pk_bf16(float lo, float hi) { unsigned r; asm volatile("v_cvt_pk_bf16_f32 %0, %1, %2" : "=v"(r) : "v"(lo), "v"(hi)); return r; }
;     __device__ __forceinline__ void operator()(const pg8::f32x4 (&acc)[2][2][4][2], const pg8::Unit& u, int wr, int wc, int fr, int fq) const {
;     ...
;                     const int i0 = 8 * (fq & 1); const bool odd = (wc & 1) != 0; const float sgn = (fq < 2) ? -1.f : 1.f;
; #pragma unroll
;                     for (int ai = 0; ai < 2; ++ai)
; #pragma unroll
;                         for (int m = 0; m < 4; ++m) { const int s = sbase + ai * HALF + m * 16;
;                             f32x4 v0 = acc[ai][bj][m][0], v1 = acc[ai][bj][m][1];
;                             if (!isctx) {
;                                 const int pos = odd ? (s & 63) : (s >> 6);
;                                 const f32x4 c0 = *(const f32x4*)(ropeC + pos * 16 + i0), c1 = *(const f32x4*)(ropeC + pos * 16 + i0 + 4);
;                                 const f32x4 s0 = *(const f32x4*)(ropeS + pos * 16 + i0), s1 = *(const f32x4*)(ropeS + pos * 16 + i0 + 4);
; #pragma unroll
;                                 for (int j = 0; j < 4; ++j) { const float p0 = __shfl_xor(v0[j], 32), p1 = __shfl_xor(v1[j], 32);
;                                     v0[j] = v0[j] * c0[j] + sgn * p0 * s0[j]; v1[j] = v1[j] * c1[j] + sgn * p1 * s1[j]; }
;                             }
;                             if (pn < 2) { v0 = v0 * QSCALE; v1 = v1 * QSCALE; }
;                             u32x4 w; w.x = cvt_pk_bf16(v0[0], v0[1]); w.y = cvt_pk_bf16(v0[2], v0[3]); w.z = cvt_pk_bf16(v1[0], v1[1]); w.w = cvt_pk_bf16(v1[2], v1[3]);
;                             const size_t grow = grow0 + ai * HALF + m * 16;
;                             if (pn < 2) *(u32x4*)(QB + grow * 512 + pn * 256 + bj * HALF + c8) = w; else *(u32x4*)(KB + grow * 128 + c8) = w; asm volatile("" ::: "memory"); }
.LBB0_195:
	v_pk_mul_f32 v[124:125], v[114:115], s[48:49] op_sel_hi:[1,0]
	v_pk_mul_f32 v[126:127], v[112:113], s[48:49] op_sel_hi:[1,0]
	v_pk_mul_f32 v[160:161], v[116:117], s[48:49] op_sel_hi:[1,0]
	v_cndmask_b32_e64 v114, v124, v114, s[8:9]
	v_cndmask_b32_e64 v116, v160, v116, s[8:9]
	v_cndmask_b32_e64 v117, v161, v117, s[8:9]
	v_cndmask_b32_e64 v112, v126, v112, s[8:9]
	v_cndmask_b32_e64 v113, v127, v113, s[8:9]
	v_cndmask_b32_e64 v115, v125, v115, s[8:9]
	v_cvt_pk_bf16_f32 v112, v112, v113
	v_cvt_pk_bf16_f32 v113, v114, v115
	v_cvt_pk_bf16_f32 v114, v116, v117
	v_lshl_add_u64 v[116:117], v[146:147], 0, 16
	v_lshlrev_b64 v[116:117], s18, v[116:117]
	v_pk_mul_f32 v[158:159], v[118:119], s[48:49] op_sel_hi:[1,0]
	v_lshl_add_u64 v[116:117], v[120:121], 0, v[116:117]
	v_cndmask_b32_e64 v118, v158, v118, s[8:9]
	v_cndmask_b32_e64 v119, v159, v119, s[8:9]
	v_cvt_pk_bf16_f32 v115, v118, v119
	global_store_dwordx4 v[116:117], v[112:115], off
	v_xor_b32_e32 v122, 32, v149
	s_and_b64 vcc, exec, s[6:7]
	s_cbranch_vccnz .LBB0_197
	v_add_u32_e32 v112, 32, v144
	v_ashrrev_i32_e32 v112, 6, v112
	v_cndmask_b32_e64 v112, v122, v112, s[10:11]
	v_lshlrev_b32_e32 v112, 4, v112
	v_ashrrev_i32_e32 v113, 31, v112
	v_lshlrev_b64 v[124:125], 2, v[112:113]
	v_lshl_add_u64 v[116:117], v[154:155], 0, v[124:125]
	global_load_dwordx4 v[112:115], v[116:117], off
	s_nop 0
	global_load_dwordx4 v[116:119], v[116:117], off offset:16
	v_lshl_add_u64 v[158:159], v[152:153], 0, v[124:125]
	global_load_dwordx4 v[124:127], v[158:159], off
	s_nop 0
	global_load_dwordx4 v[158:161], v[158:159], off offset:16
	v_and_b32_e32 v151, 64, v232
	v_xor_b32_e32 v123, 32, v232
	v_add_u32_e32 v151, 64, v151
	v_cmp_lt_i32_e32 vcc, v123, v151
	s_nop 1
	v_cndmask_b32_e32 v123, v232, v123, vcc
	v_lshlrev_b32_e32 v123, 2, v123
	ds_bpermute_b32 v162, v123, v104
	ds_bpermute_b32 v164, v123, v108
	ds_bpermute_b32 v163, v123, v105
	ds_bpermute_b32 v165, v123, v109
	s_waitcnt vmcnt(0) lgkmcnt(0)
	v_pk_mul_f32 v[104:105], v[104:105], v[112:113]
	v_pk_mul_f32 v[112:113], v[150:151], v[162:163] op_sel_hi:[0,1]
	v_pk_mul_f32 v[108:109], v[108:109], v[116:117]
	v_pk_mul_f32 v[116:117], v[150:151], v[164:165] op_sel_hi:[0,1]
	ds_bpermute_b32 v151, v123, v106
	ds_bpermute_b32 v162, v123, v110
	v_mul_f32_e32 v106, v106, v114
	v_mul_f32_e32 v110, v110, v118
	v_pk_fma_f32 v[104:105], v[124:125], v[112:113], v[104:105]
	s_waitcnt lgkmcnt(1)
	v_mul_f32_e32 v114, v150, v151
	v_mul_f32_e32 v114, v126, v114
	ds_bpermute_b32 v126, v123, v107
	ds_bpermute_b32 v123, v123, v111
	s_waitcnt lgkmcnt(2)
	v_mul_f32_e32 v118, v150, v162
	v_mul_f32_e32 v118, v160, v118
	v_mov_b32_e32 v162, v115
	s_waitcnt lgkmcnt(1)
	v_mul_f32_e32 v163, v150, v126
	v_mov_b32_e32 v126, v107
	s_waitcnt lgkmcnt(0)
	v_mul_f32_e32 v113, v150, v123
	v_mov_b32_e32 v160, v111
	v_mov_b32_e32 v112, v119
	v_pk_mul_f32 v[126:127], v[126:127], v[162:163]
	v_pk_mul_f32 v[112:113], v[160:161], v[112:113]
	v_mov_b32_e32 v107, v126
	v_mov_b32_e32 v115, v127
	v_mov_b32_e32 v111, v112
	v_mov_b32_e32 v119, v113
	v_pk_add_f32 v[106:107], v[106:107], v[114:115]
	v_pk_fma_f32 v[108:109], v[158:159], v[116:117], v[108:109]
	v_pk_add_f32 v[110:111], v[110:111], v[118:119]
.LBB0_197:
	v_pk_mul_f32 v[114:115], v[106:107], s[48:49] op_sel_hi:[1,0]
	v_pk_mul_f32 v[116:117], v[104:105], s[48:49] op_sel_hi:[1,0]
	v_pk_mul_f32 v[124:125], v[108:109], s[48:49] op_sel_hi:[1,0]
	v_cndmask_b32_e64 v106, v114, v106, s[8:9]
	v_cndmask_b32_e64 v108, v124, v108, s[8:9]
	v_cndmask_b32_e64 v109, v125, v109, s[8:9]
	v_cndmask_b32_e64 v104, v116, v104, s[8:9]
	v_cndmask_b32_e64 v105, v117, v105, s[8:9]
	v_cndmask_b32_e64 v107, v115, v107, s[8:9]
	v_cvt_pk_bf16_f32 v104, v104, v105
	v_cvt_pk_bf16_f32 v105, v106, v107
	v_cvt_pk_bf16_f32 v106, v108, v109
	v_lshl_add_u64 v[108:109], v[146:147], 0, 32
	v_lshlrev_b64 v[108:109], s18, v[108:109]
	v_pk_mul_f32 v[118:119], v[110:111], s[48:49] op_sel_hi:[1,0]
	v_lshl_add_u64 v[108:109], v[120:121], 0, v[108:109]
	v_cndmask_b32_e64 v110, v118, v110, s[8:9]
	v_cndmask_b32_e64 v111, v119, v111, s[8:9]
	v_cvt_pk_bf16_f32 v107, v110, v111
	global_store_dwordx4 v[108:109], v[104:107], off
	v_add_u32_e32 v112, 48, v148
	v_and_b32_e32 v112, 63, v112
	s_and_b64 vcc, exec, s[6:7]
	s_cbranch_vccnz .LBB0_199
	v_add_u32_e32 v104, 48, v144
	v_ashrrev_i32_e32 v104, 6, v104
	v_cndmask_b32_e64 v104, v112, v104, s[10:11]
	v_lshlrev_b32_e32 v104, 4, v104
	v_ashrrev_i32_e32 v105, 31, v104
	v_lshlrev_b64 v[114:115], 2, v[104:105]
	v_lshl_add_u64 v[108:109], v[154:155], 0, v[114:115]
	global_load_dwordx4 v[104:107], v[108:109], off
	s_nop 0
	global_load_dwordx4 v[108:111], v[108:109], off offset:16
	v_lshl_add_u64 v[118:119], v[152:153], 0, v[114:115]
	global_load_dwordx4 v[114:117], v[118:119], off
	global_load_dwordx4 v[124:127], v[118:119], off offset:16
	v_and_b32_e32 v118, 64, v232
	v_xor_b32_e32 v113, 32, v232
	v_add_u32_e32 v118, 64, v118
	v_cmp_lt_i32_e32 vcc, v113, v118
	s_nop 1
	v_cndmask_b32_e32 v113, v232, v113, vcc
	v_lshlrev_b32_e32 v113, 2, v113
	ds_bpermute_b32 v118, v113, v96
	ds_bpermute_b32 v119, v113, v97
	ds_bpermute_b32 v158, v113, v100
	ds_bpermute_b32 v159, v113, v101
	s_waitcnt vmcnt(0) lgkmcnt(0)
	v_pk_mul_f32 v[96:97], v[96:97], v[104:105]
	v_pk_mul_f32 v[104:105], v[150:151], v[118:119] op_sel_hi:[0,1]
	ds_bpermute_b32 v118, v113, v98
	ds_bpermute_b32 v119, v113, v102
	v_mul_f32_e32 v98, v98, v106
	v_mul_f32_e32 v102, v102, v110
	v_pk_fma_f32 v[96:97], v[114:115], v[104:105], v[96:97]
	s_waitcnt lgkmcnt(1)
	v_mul_f32_e32 v106, v150, v118
	v_mul_f32_e32 v106, v116, v106
	ds_bpermute_b32 v116, v113, v99
	ds_bpermute_b32 v113, v113, v103
	s_waitcnt lgkmcnt(2)
	v_mul_f32_e32 v110, v150, v119
	v_mul_f32_e32 v110, v126, v110
	v_mov_b32_e32 v118, v107
	s_waitcnt lgkmcnt(1)
	v_mul_f32_e32 v119, v150, v116
	v_mov_b32_e32 v116, v99
	s_waitcnt lgkmcnt(0)
	v_mul_f32_e32 v105, v150, v113
	v_mov_b32_e32 v126, v103
	v_mov_b32_e32 v104, v111
	v_pk_mul_f32 v[116:117], v[116:117], v[118:119]
	v_pk_mul_f32 v[104:105], v[126:127], v[104:105]
	v_pk_mul_f32 v[100:101], v[100:101], v[108:109]
	v_pk_mul_f32 v[108:109], v[150:151], v[158:159] op_sel_hi:[0,1]
	v_mov_b32_e32 v99, v116
	v_mov_b32_e32 v107, v117
	v_mov_b32_e32 v103, v104
	v_mov_b32_e32 v111, v105
	v_pk_add_f32 v[98:99], v[98:99], v[106:107]
	v_pk_fma_f32 v[100:101], v[124:125], v[108:109], v[100:101]
	v_pk_add_f32 v[102:103], v[102:103], v[110:111]
; __device__ __forceinline__ unsigned cvt_pk_bf16(float lo, float hi) { unsigned r; asm volatile("v_cvt_pk_bf16_f32 %0, %1, %2" : "=v"(r) : "v"(lo), "v"(hi)); return r; }
;     __device__ __forceinline__ void operator()(const pg8::f32x4 (&acc)[2][2][4][2], const pg8::Unit& u, int wr, int wc, int fr, int fq) const {
;     ...
;                     const int i0 = 8 * (fq & 1); const bool odd = (wc & 1) != 0; const float sgn = (fq < 2) ? -1.f : 1.f;
; #pragma unroll
;                     for (int ai = 0; ai < 2; ++ai)
; #pragma unroll
;                         for (int m = 0; m < 4; ++m) { const int s = sbase + ai * HALF + m * 16;
;                             f32x4 v0 = acc[ai][bj][m][0], v1 = acc[ai][bj][m][1];
;                             if (!isctx) {
;                                 const int pos = odd ? (s & 63) : (s >> 6);
;                                 const f32x4 c0 = *(const f32x4*)(ropeC + pos * 16 + i0), c1 = *(const f32x4*)(ropeC + pos * 16 + i0 + 4);
;                                 const f32x4 s0 = *(const f32x4*)(ropeS + pos * 16 + i0), s1 = *(const f32x4*)(ropeS + pos * 16 + i0 + 4);
; #pragma unroll
;                                 for (int j = 0; j < 4; ++j) { const float p0 = __shfl_xor(v0[j], 32), p1 = __shfl_xor(v1[j], 32);
;                                     v0[j] = v0[j] * c0[j] + sgn * p0 * s0[j]; v1[j] = v1[j] * c1[j] + sgn * p1 * s1[j]; }
;                             }
;                             if (pn < 2) { v0 = v0 * QSCALE; v1 = v1 * QSCALE; }
;                             u32x4 w; w.x = cvt_pk_bf16(v0[0], v0[1]); w.y = cvt_pk_bf16(v0[2], v0[3]); w.z = cvt_pk_bf16(v1[0], v1[1]); w.w = cvt_pk_bf16(v1[2], v1[3]);
;                             const size_t grow = grow0 + ai * HALF + m * 16;
;                             if (pn < 2) *(u32x4*)(QB + grow * 512 + pn * 256 + bj * HALF + c8) = w; else *(u32x4*)(KB + grow * 128 + c8) = w; asm volatile("" ::: "memory"); }
.LBB0_199:
	v_pk_mul_f32 v[104:105], v[98:99], s[48:49] op_sel_hi:[1,0]
	v_pk_mul_f32 v[106:107], v[96:97], s[48:49] op_sel_hi:[1,0]
	v_pk_mul_f32 v[110:111], v[100:101], s[48:49] op_sel_hi:[1,0]
	v_cndmask_b32_e64 v98, v104, v98, s[8:9]
	v_cndmask_b32_e64 v100, v110, v100, s[8:9]
	v_cndmask_b32_e64 v101, v111, v101, s[8:9]
	v_cndmask_b32_e64 v96, v106, v96, s[8:9]
	v_cndmask_b32_e64 v97, v107, v97, s[8:9]
	v_cndmask_b32_e64 v99, v105, v99, s[8:9]
	v_cvt_pk_bf16_f32 v96, v96, v97
	v_cvt_pk_bf16_f32 v97, v98, v99
	v_cvt_pk_bf16_f32 v98, v100, v101
	v_lshl_add_u64 v[100:101], v[146:147], 0, 48
	v_lshlrev_b64 v[100:101], s18, v[100:101]
	v_pk_mul_f32 v[108:109], v[102:103], s[48:49] op_sel_hi:[1,0]
	v_lshl_add_u64 v[100:101], v[120:121], 0, v[100:101]
	v_cndmask_b32_e64 v102, v108, v102, s[8:9]
	v_cndmask_b32_e64 v103, v109, v103, s[8:9]
	v_cvt_pk_bf16_f32 v99, v102, v103
	global_store_dwordx4 v[100:101], v[96:99], off
	s_and_b64 vcc, exec, s[6:7]
	s_cbranch_vccnz .LBB0_201
	v_add_u32_e32 v96, 0x80, v144
	v_ashrrev_i32_e32 v96, 6, v96
	v_cndmask_b32_e64 v96, v149, v96, s[10:11]
	v_lshlrev_b32_e32 v96, 4, v96
	v_ashrrev_i32_e32 v97, 31, v96
	v_lshlrev_b64 v[104:105], 2, v[96:97]
	v_lshl_add_u64 v[100:101], v[154:155], 0, v[104:105]
	global_load_dwordx4 v[96:99], v[100:101], off
	s_nop 0
	global_load_dwordx4 v[100:103], v[100:101], off offset:16
	v_lshl_add_u64 v[108:109], v[152:153], 0, v[104:105]
	global_load_dwordx4 v[104:107], v[108:109], off
	s_nop 0
	global_load_dwordx4 v[108:111], v[108:109], off offset:16
	v_and_b32_e32 v114, 64, v232
	v_xor_b32_e32 v113, 32, v232
	v_add_u32_e32 v114, 64, v114
	v_cmp_lt_i32_e32 vcc, v113, v114
	s_nop 1
	v_cndmask_b32_e32 v113, v232, v113, vcc
	v_lshlrev_b32_e32 v113, 2, v113
	ds_bpermute_b32 v114, v113, v88
	ds_bpermute_b32 v115, v113, v89
	ds_bpermute_b32 v116, v113, v92
	ds_bpermute_b32 v117, v113, v93
	s_waitcnt vmcnt(0) lgkmcnt(0)
	v_pk_mul_f32 v[88:89], v[88:89], v[96:97]
	v_pk_mul_f32 v[96:97], v[150:151], v[114:115] op_sel_hi:[0,1]
	ds_bpermute_b32 v114, v113, v90
	ds_bpermute_b32 v115, v113, v94
	v_mul_f32_e32 v90, v90, v98
	v_mul_f32_e32 v94, v94, v102
	v_pk_fma_f32 v[88:89], v[104:105], v[96:97], v[88:89]
	s_waitcnt lgkmcnt(1)
	v_mul_f32_e32 v98, v150, v114
	s_waitcnt lgkmcnt(0)
	v_mul_f32_e32 v102, v150, v115
	v_mul_f32_e32 v98, v106, v98
	v_mul_f32_e32 v102, v110, v102
	ds_bpermute_b32 v106, v113, v91
	ds_bpermute_b32 v110, v113, v95
	v_mov_b32_e32 v114, v99
	v_mov_b32_e32 v96, v103
	v_pk_mul_f32 v[92:93], v[92:93], v[100:101]
	s_waitcnt lgkmcnt(1)
	v_mul_f32_e32 v115, v150, v106
	v_mov_b32_e32 v106, v91
	s_waitcnt lgkmcnt(0)
	v_mul_f32_e32 v97, v150, v110
	v_mov_b32_e32 v110, v95
	v_pk_mul_f32 v[106:107], v[106:107], v[114:115]
	v_pk_mul_f32 v[96:97], v[110:111], v[96:97]
	v_pk_mul_f32 v[100:101], v[150:151], v[116:117] op_sel_hi:[0,1]
	v_mov_b32_e32 v91, v106
	v_mov_b32_e32 v99, v107
	v_mov_b32_e32 v95, v96
	v_mov_b32_e32 v103, v97
	v_pk_add_f32 v[90:91], v[90:91], v[98:99]
	v_pk_fma_f32 v[92:93], v[108:109], v[100:101], v[92:93]
	v_pk_add_f32 v[94:95], v[94:95], v[102:103]
.LBB0_201:
	v_pk_mul_f32 v[98:99], v[90:91], s[48:49] op_sel_hi:[1,0]
	v_pk_mul_f32 v[100:101], v[88:89], s[48:49] op_sel_hi:[1,0]
	v_pk_mul_f32 v[104:105], v[92:93], s[48:49] op_sel_hi:[1,0]
	v_lshl_add_u64 v[96:97], v[146:147], 0, s[44:45]
	v_cndmask_b32_e64 v92, v104, v92, s[8:9]
	v_cndmask_b32_e64 v93, v105, v93, s[8:9]
	v_cndmask_b32_e64 v90, v98, v90, s[8:9]
	v_cndmask_b32_e64 v88, v100, v88, s[8:9]
	v_cndmask_b32_e64 v89, v101, v89, s[8:9]
	v_cndmask_b32_e64 v91, v99, v91, s[8:9]
	v_cvt_pk_bf16_f32 v88, v88, v89
	v_cvt_pk_bf16_f32 v89, v90, v91
	v_cvt_pk_bf16_f32 v90, v92, v93
	v_lshlrev_b64 v[92:93], s18, v[96:97]
	v_pk_mul_f32 v[102:103], v[94:95], s[48:49] op_sel_hi:[1,0]
	v_lshl_add_u64 v[92:93], v[120:121], 0, v[92:93]
	v_cndmask_b32_e64 v94, v102, v94, s[8:9]
	v_cndmask_b32_e64 v95, v103, v95, s[8:9]
	v_cvt_pk_bf16_f32 v91, v94, v95
	global_store_dwordx4 v[92:93], v[88:91], off
	s_and_b64 vcc, exec, s[6:7]
	s_cbranch_vccnz .LBB0_203
	v_add_u32_e32 v88, 0x90, v144
	v_ashrrev_i32_e32 v88, 6, v88
	v_cndmask_b32_e64 v88, v145, v88, s[10:11]
	v_lshlrev_b32_e32 v88, 4, v88
	v_ashrrev_i32_e32 v89, 31, v88
	v_lshlrev_b64 v[96:97], 2, v[88:89]
	v_lshl_add_u64 v[92:93], v[154:155], 0, v[96:97]
	global_load_dwordx4 v[88:91], v[92:93], off
	s_nop 0
	global_load_dwordx4 v[92:95], v[92:93], off offset:16
	v_lshl_add_u64 v[100:101], v[152:153], 0, v[96:97]
	global_load_dwordx4 v[96:99], v[100:101], off
	s_nop 0
	global_load_dwordx4 v[100:103], v[100:101], off offset:16
	v_and_b32_e32 v105, 64, v232
	v_xor_b32_e32 v104, 32, v232
	v_add_u32_e32 v105, 64, v105
	v_cmp_lt_i32_e32 vcc, v104, v105
	s_nop 1
	v_cndmask_b32_e32 v104, v232, v104, vcc
	v_lshlrev_b32_e32 v108, 2, v104
	ds_bpermute_b32 v104, v108, v80
	ds_bpermute_b32 v105, v108, v81
	ds_bpermute_b32 v106, v108, v84
	ds_bpermute_b32 v107, v108, v85
	s_waitcnt vmcnt(0) lgkmcnt(0)
	v_pk_mul_f32 v[80:81], v[80:81], v[88:89]
	v_pk_mul_f32 v[88:89], v[150:151], v[104:105] op_sel_hi:[0,1]
	ds_bpermute_b32 v104, v108, v82
	ds_bpermute_b32 v105, v108, v86
	v_mul_f32_e32 v82, v82, v90
	v_mul_f32_e32 v86, v86, v94
	v_pk_fma_f32 v[80:81], v[96:97], v[88:89], v[80:81]
	s_waitcnt lgkmcnt(1)
	v_mul_f32_e32 v90, v150, v104
	s_waitcnt lgkmcnt(0)
	v_mul_f32_e32 v94, v150, v105
	v_mul_f32_e32 v90, v98, v90
	v_mul_f32_e32 v94, v102, v94
	ds_bpermute_b32 v98, v108, v83
	ds_bpermute_b32 v102, v108, v87
	v_mov_b32_e32 v104, v91
	v_mov_b32_e32 v88, v95
	v_pk_mul_f32 v[84:85], v[84:85], v[92:93]
	s_waitcnt lgkmcnt(1)
	v_mul_f32_e32 v105, v150, v98
	v_mov_b32_e32 v98, v83
	s_waitcnt lgkmcnt(0)
	v_mul_f32_e32 v89, v150, v102
	v_mov_b32_e32 v102, v87
	v_pk_mul_f32 v[98:99], v[98:99], v[104:105]
	v_pk_mul_f32 v[88:89], v[102:103], v[88:89]
	v_pk_mul_f32 v[92:93], v[150:151], v[106:107] op_sel_hi:[0,1]
	v_mov_b32_e32 v83, v98
	v_mov_b32_e32 v91, v99
	v_mov_b32_e32 v87, v88
	v_mov_b32_e32 v95, v89
	v_pk_add_f32 v[82:83], v[82:83], v[90:91]
	v_pk_fma_f32 v[84:85], v[100:101], v[92:93], v[84:85]
	v_pk_add_f32 v[86:87], v[86:87], v[94:95]
; __device__ __forceinline__ unsigned cvt_pk_bf16(float lo, float hi) { unsigned r; asm volatile("v_cvt_pk_bf16_f32 %0, %1, %2" : "=v"(r) : "v"(lo), "v"(hi)); return r; }
;     __device__ __forceinline__ void operator()(const pg8::f32x4 (&acc)[2][2][4][2], const pg8::Unit& u, int wr, int wc, int fr, int fq) const {
;     ...
;                     const int i0 = 8 * (fq & 1); const bool odd = (wc & 1) != 0; const float sgn = (fq < 2) ? -1.f : 1.f;
; #pragma unroll
;                     for (int ai = 0; ai < 2; ++ai)
; #pragma unroll
;                         for (int m = 0; m < 4; ++m) { const int s = sbase + ai * HALF + m * 16;
;                             f32x4 v0 = acc[ai][bj][m][0], v1 = acc[ai][bj][m][1];
;                             if (!isctx) {
;                                 const int pos = odd ? (s & 63) : (s >> 6);
;                                 const f32x4 c0 = *(const f32x4*)(ropeC + pos * 16 + i0), c1 = *(const f32x4*)(ropeC + pos * 16 + i0 + 4);
;                                 const f32x4 s0 = *(const f32x4*)(ropeS + pos * 16 + i0), s1 = *(const f32x4*)(ropeS + pos * 16 + i0 + 4);
; #pragma unroll
;                                 for (int j = 0; j < 4; ++j) { const float p0 = __shfl_xor(v0[j], 32), p1 = __shfl_xor(v1[j], 32);
;                                     v0[j] = v0[j] * c0[j] + sgn * p0 * s0[j]; v1[j] = v1[j] * c1[j] + sgn * p1 * s1[j]; }
;                             }
;                             if (pn < 2) { v0 = v0 * QSCALE; v1 = v1 * QSCALE; }
;                             u32x4 w; w.x = cvt_pk_bf16(v0[0], v0[1]); w.y = cvt_pk_bf16(v0[2], v0[3]); w.z = cvt_pk_bf16(v1[0], v1[1]); w.w = cvt_pk_bf16(v1[2], v1[3]);
;                             const size_t grow = grow0 + ai * HALF + m * 16;
;                             if (pn < 2) *(u32x4*)(QB + grow * 512 + pn * 256 + bj * HALF + c8) = w; else *(u32x4*)(KB + grow * 128 + c8) = w; asm volatile("" ::: "memory"); }
.LBB0_203:
	v_pk_mul_f32 v[88:89], v[82:83], s[48:49] op_sel_hi:[1,0]
	v_pk_mul_f32 v[90:91], v[80:81], s[48:49] op_sel_hi:[1,0]
	v_pk_mul_f32 v[94:95], v[84:85], s[48:49] op_sel_hi:[1,0]
	v_cndmask_b32_e64 v82, v88, v82, s[8:9]
	v_cndmask_b32_e64 v84, v94, v84, s[8:9]
	v_cndmask_b32_e64 v85, v95, v85, s[8:9]
	v_cndmask_b32_e64 v80, v90, v80, s[8:9]
	v_cndmask_b32_e64 v81, v91, v81, s[8:9]
	s_mov_b64 s[24:25], 0x90
	v_cndmask_b32_e64 v83, v89, v83, s[8:9]
	v_cvt_pk_bf16_f32 v80, v80, v81
	v_cvt_pk_bf16_f32 v81, v82, v83
	v_cvt_pk_bf16_f32 v82, v84, v85
	v_lshl_add_u64 v[84:85], v[146:147], 0, s[24:25]
	v_lshlrev_b64 v[84:85], s18, v[84:85]
	v_pk_mul_f32 v[92:93], v[86:87], s[48:49] op_sel_hi:[1,0]
	v_lshl_add_u64 v[84:85], v[120:121], 0, v[84:85]
	v_cndmask_b32_e64 v86, v92, v86, s[8:9]
	v_cndmask_b32_e64 v87, v93, v87, s[8:9]
	v_cvt_pk_bf16_f32 v83, v86, v87
	global_store_dwordx4 v[84:85], v[80:83], off
	s_and_b64 vcc, exec, s[6:7]
	s_cbranch_vccnz .LBB0_205
	v_add_u32_e32 v80, 0xa0, v144
	v_ashrrev_i32_e32 v80, 6, v80
	v_cndmask_b32_e64 v80, v122, v80, s[10:11]
	v_lshlrev_b32_e32 v80, 4, v80
	v_ashrrev_i32_e32 v81, 31, v80
	v_lshlrev_b64 v[88:89], 2, v[80:81]
	v_lshl_add_u64 v[84:85], v[154:155], 0, v[88:89]
	global_load_dwordx4 v[80:83], v[84:85], off
	s_nop 0
	global_load_dwordx4 v[84:87], v[84:85], off offset:16
	v_lshl_add_u64 v[92:93], v[152:153], 0, v[88:89]
	global_load_dwordx4 v[88:91], v[92:93], off
	s_nop 0
	global_load_dwordx4 v[92:95], v[92:93], off offset:16
	v_and_b32_e32 v97, 64, v232
	v_xor_b32_e32 v96, 32, v232
	v_add_u32_e32 v97, 64, v97
	v_cmp_lt_i32_e32 vcc, v96, v97
	s_nop 1
	v_cndmask_b32_e32 v96, v232, v96, vcc
	v_lshlrev_b32_e32 v100, 2, v96
	ds_bpermute_b32 v96, v100, v72
	ds_bpermute_b32 v97, v100, v73
	ds_bpermute_b32 v98, v100, v76
	ds_bpermute_b32 v99, v100, v77
	s_waitcnt vmcnt(0) lgkmcnt(0)
	v_pk_mul_f32 v[72:73], v[72:73], v[80:81]
	v_pk_mul_f32 v[80:81], v[150:151], v[96:97] op_sel_hi:[0,1]
	ds_bpermute_b32 v96, v100, v74
	ds_bpermute_b32 v97, v100, v78
	v_mul_f32_e32 v74, v74, v82
	v_mul_f32_e32 v78, v78, v86
	v_pk_fma_f32 v[72:73], v[88:89], v[80:81], v[72:73]
	s_waitcnt lgkmcnt(1)
	v_mul_f32_e32 v82, v150, v96
	s_waitcnt lgkmcnt(0)
	v_mul_f32_e32 v86, v150, v97
	v_mul_f32_e32 v82, v90, v82
	v_mul_f32_e32 v86, v94, v86
	ds_bpermute_b32 v90, v100, v75
	ds_bpermute_b32 v94, v100, v79
	v_mov_b32_e32 v96, v83
	v_mov_b32_e32 v80, v87
	v_pk_mul_f32 v[76:77], v[76:77], v[84:85]
	s_waitcnt lgkmcnt(1)
	v_mul_f32_e32 v97, v150, v90
	v_mov_b32_e32 v90, v75
	s_waitcnt lgkmcnt(0)
	v_mul_f32_e32 v81, v150, v94
	v_mov_b32_e32 v94, v79
	v_pk_mul_f32 v[90:91], v[90:91], v[96:97]
	v_pk_mul_f32 v[80:81], v[94:95], v[80:81]
	v_pk_mul_f32 v[84:85], v[150:151], v[98:99] op_sel_hi:[0,1]
	v_mov_b32_e32 v75, v90
	v_mov_b32_e32 v83, v91
	v_mov_b32_e32 v79, v80
	v_mov_b32_e32 v87, v81
	v_pk_add_f32 v[74:75], v[74:75], v[82:83]
	v_pk_fma_f32 v[76:77], v[92:93], v[84:85], v[76:77]
	v_pk_add_f32 v[78:79], v[78:79], v[86:87]
.LBB0_205:
	v_pk_mul_f32 v[80:81], v[74:75], s[48:49] op_sel_hi:[1,0]
	v_pk_mul_f32 v[82:83], v[72:73], s[48:49] op_sel_hi:[1,0]
	v_pk_mul_f32 v[86:87], v[76:77], s[48:49] op_sel_hi:[1,0]
	v_cndmask_b32_e64 v74, v80, v74, s[8:9]
	v_cndmask_b32_e64 v76, v86, v76, s[8:9]
	v_cndmask_b32_e64 v77, v87, v77, s[8:9]
	v_cndmask_b32_e64 v72, v82, v72, s[8:9]
	v_cndmask_b32_e64 v73, v83, v73, s[8:9]
	s_mov_b64 s[24:25], 0xa0
	v_cndmask_b32_e64 v75, v81, v75, s[8:9]
	v_cvt_pk_bf16_f32 v72, v72, v73
	v_cvt_pk_bf16_f32 v73, v74, v75
	v_cvt_pk_bf16_f32 v74, v76, v77
	v_lshl_add_u64 v[76:77], v[146:147], 0, s[24:25]
	v_lshlrev_b64 v[76:77], s18, v[76:77]
	v_pk_mul_f32 v[84:85], v[78:79], s[48:49] op_sel_hi:[1,0]
	v_lshl_add_u64 v[76:77], v[120:121], 0, v[76:77]
	v_cndmask_b32_e64 v78, v84, v78, s[8:9]
	v_cndmask_b32_e64 v79, v85, v79, s[8:9]
	v_cvt_pk_bf16_f32 v75, v78, v79
	global_store_dwordx4 v[76:77], v[72:75], off
	s_and_b64 vcc, exec, s[6:7]
	s_cbranch_vccnz .LBB0_207
	v_add_u32_e32 v72, 0xb0, v144
	v_ashrrev_i32_e32 v72, 6, v72
	v_cndmask_b32_e64 v72, v112, v72, s[10:11]
	v_lshlrev_b32_e32 v72, 4, v72
	v_ashrrev_i32_e32 v73, 31, v72
	v_lshlrev_b64 v[80:81], 2, v[72:73]
	v_lshl_add_u64 v[76:77], v[154:155], 0, v[80:81]
	global_load_dwordx4 v[72:75], v[76:77], off
	s_nop 0
	global_load_dwordx4 v[76:79], v[76:77], off offset:16
	v_lshl_add_u64 v[84:85], v[152:153], 0, v[80:81]
	global_load_dwordx4 v[80:83], v[84:85], off
	s_nop 0
	global_load_dwordx4 v[84:87], v[84:85], off offset:16
	v_and_b32_e32 v89, 64, v232
	v_xor_b32_e32 v88, 32, v232
	v_add_u32_e32 v89, 64, v89
	v_cmp_lt_i32_e32 vcc, v88, v89
	s_nop 1
	v_cndmask_b32_e32 v88, v232, v88, vcc
	v_lshlrev_b32_e32 v92, 2, v88
	ds_bpermute_b32 v88, v92, v64
	ds_bpermute_b32 v89, v92, v65
	ds_bpermute_b32 v90, v92, v68
	ds_bpermute_b32 v91, v92, v69
	s_waitcnt vmcnt(0) lgkmcnt(0)
	v_pk_mul_f32 v[64:65], v[64:65], v[72:73]
	v_pk_mul_f32 v[72:73], v[150:151], v[88:89] op_sel_hi:[0,1]
	ds_bpermute_b32 v88, v92, v66
	ds_bpermute_b32 v89, v92, v70
	v_mul_f32_e32 v66, v66, v74
	v_mul_f32_e32 v70, v70, v78
	v_pk_fma_f32 v[64:65], v[80:81], v[72:73], v[64:65]
	s_waitcnt lgkmcnt(1)
	v_mul_f32_e32 v74, v150, v88
	s_waitcnt lgkmcnt(0)
	v_mul_f32_e32 v78, v150, v89
	v_mul_f32_e32 v74, v82, v74
	v_mul_f32_e32 v78, v86, v78
	ds_bpermute_b32 v82, v92, v67
	ds_bpermute_b32 v86, v92, v71
	v_mov_b32_e32 v88, v75
	v_mov_b32_e32 v72, v79
	v_pk_mul_f32 v[68:69], v[68:69], v[76:77]
	s_waitcnt lgkmcnt(1)
	v_mul_f32_e32 v89, v150, v82
	v_mov_b32_e32 v82, v67
	s_waitcnt lgkmcnt(0)
	v_mul_f32_e32 v73, v150, v86
	v_mov_b32_e32 v86, v71
	v_pk_mul_f32 v[82:83], v[82:83], v[88:89]
	v_pk_mul_f32 v[72:73], v[86:87], v[72:73]
	v_pk_mul_f32 v[76:77], v[150:151], v[90:91] op_sel_hi:[0,1]
	v_mov_b32_e32 v67, v82
	v_mov_b32_e32 v75, v83
	v_mov_b32_e32 v71, v72
	v_mov_b32_e32 v79, v73
	v_pk_add_f32 v[66:67], v[66:67], v[74:75]
	v_pk_fma_f32 v[68:69], v[84:85], v[76:77], v[68:69]
	v_pk_add_f32 v[70:71], v[70:71], v[78:79]
; __device__ __forceinline__ unsigned cvt_pk_bf16(float lo, float hi) { unsigned r; asm volatile("v_cvt_pk_bf16_f32 %0, %1, %2" : "=v"(r) : "v"(lo), "v"(hi)); return r; }
;     __device__ __forceinline__ void operator()(const pg8::f32x4 (&acc)[2][2][4][2], const pg8::Unit& u, int wr, int wc, int fr, int fq) const {
;     ...
;                     const int i0 = 8 * (fq & 1); const bool odd = (wc & 1) != 0; const float sgn = (fq < 2) ? -1.f : 1.f;
; #pragma unroll
;                     for (int ai = 0; ai < 2; ++ai)
; #pragma unroll
;                         for (int m = 0; m < 4; ++m) { const int s = sbase + ai * HALF + m * 16;
;                             f32x4 v0 = acc[ai][bj][m][0], v1 = acc[ai][bj][m][1];
;                             if (!isctx) {
;                                 const int pos = odd ? (s & 63) : (s >> 6);
;                                 const f32x4 c0 = *(const f32x4*)(ropeC + pos * 16 + i0), c1 = *(const f32x4*)(ropeC + pos * 16 + i0 + 4);
;                                 const f32x4 s0 = *(const f32x4*)(ropeS + pos * 16 + i0), s1 = *(const f32x4*)(ropeS + pos * 16 + i0 + 4);
; #pragma unroll
;                                 for (int j = 0; j < 4; ++j) { const float p0 = __shfl_xor(v0[j], 32), p1 = __shfl_xor(v1[j], 32);
;                                     v0[j] = v0[j] * c0[j] + sgn * p0 * s0[j]; v1[j] = v1[j] * c1[j] + sgn * p1 * s1[j]; }
;                             }
;                             if (pn < 2) { v0 = v0 * QSCALE; v1 = v1 * QSCALE; }
;                             u32x4 w; w.x = cvt_pk_bf16(v0[0], v0[1]); w.y = cvt_pk_bf16(v0[2], v0[3]); w.z = cvt_pk_bf16(v1[0], v1[1]); w.w = cvt_pk_bf16(v1[2], v1[3]);
;                             const size_t grow = grow0 + ai * HALF + m * 16;
;                             if (pn < 2) *(u32x4*)(QB + grow * 512 + pn * 256 + bj * HALF + c8) = w; else *(u32x4*)(KB + grow * 128 + c8) = w; asm volatile("" ::: "memory"); }
.LBB0_207:
	v_pk_mul_f32 v[72:73], v[66:67], s[48:49] op_sel_hi:[1,0]
	v_pk_mul_f32 v[74:75], v[64:65], s[48:49] op_sel_hi:[1,0]
	v_pk_mul_f32 v[76:77], v[70:71], s[48:49] op_sel_hi:[1,0]
	v_pk_mul_f32 v[78:79], v[68:69], s[48:49] op_sel_hi:[1,0]
	v_cndmask_b32_e64 v70, v76, v70, s[8:9]
	v_cndmask_b32_e64 v71, v77, v71, s[8:9]
	v_cndmask_b32_e64 v68, v78, v68, s[8:9]
	v_cndmask_b32_e64 v69, v79, v69, s[8:9]
	v_cndmask_b32_e64 v66, v72, v66, s[8:9]
	v_cndmask_b32_e64 v67, v73, v67, s[8:9]
	v_cndmask_b32_e64 v64, v74, v64, s[8:9]
	v_cndmask_b32_e64 v65, v75, v65, s[8:9]
	s_mov_b64 s[8:9], 0xb0
	v_cvt_pk_bf16_f32 v64, v64, v65
	v_cvt_pk_bf16_f32 v65, v66, v67
	v_cvt_pk_bf16_f32 v66, v68, v69
	v_lshl_add_u64 v[68:69], v[146:147], 0, s[8:9]
	v_lshlrev_b64 v[68:69], s18, v[68:69]
	v_lshl_add_u64 v[68:69], v[120:121], 0, v[68:69]
	v_cvt_pk_bf16_f32 v67, v70, v71
	global_store_dwordx4 v[68:69], v[64:67], off
	s_andn2_b64 vcc, exec, s[70:71]
	s_mov_b64 s[8:9], -1
	s_cbranch_vccnz .LBB0_233
	s_and_b64 vcc, exec, s[6:7]
	s_cbranch_vccnz .LBB0_210
	v_ashrrev_i32_e32 v64, 6, v144
	v_cndmask_b32_e64 v64, v149, v64, s[10:11]
	v_lshlrev_b32_e32 v64, 4, v64
	v_ashrrev_i32_e32 v65, 31, v64
	v_lshlrev_b64 v[72:73], 2, v[64:65]
	v_lshl_add_u64 v[68:69], v[154:155], 0, v[72:73]
	v_lshl_add_u64 v[76:77], v[152:153], 0, v[72:73]
	global_load_dwordx4 v[64:67], v[68:69], off
	s_nop 0
	global_load_dwordx4 v[68:71], v[68:69], off offset:16
	s_nop 0
	global_load_dwordx4 v[72:75], v[76:77], off
	s_nop 0
	global_load_dwordx4 v[76:79], v[76:77], off offset:16
	v_and_b32_e32 v81, 64, v232
	v_xor_b32_e32 v80, 32, v232
	v_add_u32_e32 v81, 64, v81
	v_cmp_lt_i32_e32 vcc, v80, v81
	s_waitcnt vmcnt(0) lgkmcnt(0)
	v_pk_mul_f32 v[64:65], v[60:61], v[64:65]
	v_cndmask_b32_e32 v80, v232, v80, vcc
	v_lshlrev_b32_e32 v85, 2, v80
	ds_bpermute_b32 v84, v85, v62
	ds_bpermute_b32 v86, v85, v58
	ds_bpermute_b32 v80, v85, v60
	ds_bpermute_b32 v81, v85, v61
	ds_bpermute_b32 v82, v85, v56
	s_waitcnt lgkmcnt(4)
	v_mul_f32_e32 v84, v150, v84
	v_mul_f32_e32 v84, v74, v84
	s_waitcnt lgkmcnt(3)
	v_mul_f32_e32 v74, v150, v86
	v_mul_f32_e32 v86, v78, v74
	ds_bpermute_b32 v74, v85, v63
	ds_bpermute_b32 v78, v85, v59
	ds_bpermute_b32 v83, v85, v57
	s_waitcnt lgkmcnt(4)
	v_pk_mul_f32 v[80:81], v[150:151], v[80:81] op_sel_hi:[0,1]
	v_mov_b32_e32 v88, v67
	s_waitcnt lgkmcnt(2)
	v_mul_f32_e32 v89, v150, v74
	v_mov_b32_e32 v74, v63
	v_pk_fma_f32 v[64:65], v[72:73], v[80:81], v[64:65]
	s_waitcnt lgkmcnt(1)
	v_mul_f32_e32 v73, v150, v78
	v_mov_b32_e32 v78, v59
	v_mov_b32_e32 v72, v71
	v_pk_mul_f32 v[74:75], v[74:75], v[88:89]
	v_pk_mul_f32 v[72:73], v[78:79], v[72:73]
	v_pk_mul_f32 v[68:69], v[56:57], v[68:69]
	s_waitcnt lgkmcnt(0)
	v_pk_mul_f32 v[82:83], v[150:151], v[82:83] op_sel_hi:[0,1]
	v_mul_f32_e32 v66, v62, v66
	v_mul_f32_e32 v70, v58, v70
	v_mov_b32_e32 v67, v74
	v_mov_b32_e32 v85, v75
	v_mov_b32_e32 v71, v72
	v_mov_b32_e32 v87, v73
	v_pk_add_f32 v[66:67], v[66:67], v[84:85]
	v_pk_fma_f32 v[68:69], v[76:77], v[82:83], v[68:69]
	v_pk_add_f32 v[70:71], v[70:71], v[86:87]
	s_branch .LBB0_211

; __device__ __forceinline__ unsigned cvt_pk_bf16(float lo, float hi) { unsigned r; asm volatile("v_cvt_pk_bf16_f32 %0, %1, %2" : "=v"(r) : "v"(lo), "v"(hi)); return r; }
;     __device__ __forceinline__ void operator()(const pg8::f32x4 (&acc)[2][2][4][2], const pg8::Unit& u, int wr, int wc, int fr, int fq) const {
;     ...
;                     const int i0 = 8 * (fq & 1); const bool odd = (wc & 1) != 0; const float sgn = (fq < 2) ? -1.f : 1.f;
; #pragma unroll
;                     for (int ai = 0; ai < 2; ++ai)
; #pragma unroll
;                         for (int m = 0; m < 4; ++m) { const int s = sbase + ai * HALF + m * 16;
;                             f32x4 v0 = acc[ai][bj][m][0], v1 = acc[ai][bj][m][1];
;                             if (!isctx) {
;                                 const int pos = odd ? (s & 63) : (s >> 6);
;                                 const f32x4 c0 = *(const f32x4*)(ropeC + pos * 16 + i0), c1 = *(const f32x4*)(ropeC + pos * 16 + i0 + 4);
;                                 const f32x4 s0 = *(const f32x4*)(ropeS + pos * 16 + i0), s1 = *(const f32x4*)(ropeS + pos * 16 + i0 + 4);
; #pragma unroll
;                                 for (int j = 0; j < 4; ++j) { const float p0 = __shfl_xor(v0[j], 32), p1 = __shfl_xor(v1[j], 32);
;                                     v0[j] = v0[j] * c0[j] + sgn * p0 * s0[j]; v1[j] = v1[j] * c1[j] + sgn * p1 * s1[j]; }
;                             }
;                             if (pn < 2) { v0 = v0 * QSCALE; v1 = v1 * QSCALE; }
;                             u32x4 w; w.x = cvt_pk_bf16(v0[0], v0[1]); w.y = cvt_pk_bf16(v0[2], v0[3]); w.z = cvt_pk_bf16(v1[0], v1[1]); w.w = cvt_pk_bf16(v1[2], v1[3]);
;                             const size_t grow = grow0 + ai * HALF + m * 16;
;                             if (pn < 2) *(u32x4*)(QB + grow * 512 + pn * 256 + bj * HALF + c8) = w; else *(u32x4*)(KB + grow * 128 + c8) = w; asm volatile("" ::: "memory"); }
.LBB0_211:
	v_pk_mul_f32 v[66:67], v[66:67], s[48:49] op_sel_hi:[1,0]
	v_pk_mul_f32 v[64:65], v[64:65], s[48:49] op_sel_hi:[1,0]
	v_pk_mul_f32 v[68:69], v[68:69], s[48:49] op_sel_hi:[1,0]
	v_cvt_pk_bf16_f32 v64, v64, v65
	v_cvt_pk_bf16_f32 v65, v66, v67
	v_pk_mul_f32 v[70:71], v[70:71], s[48:49] op_sel_hi:[1,0]
	v_cvt_pk_bf16_f32 v66, v68, v69
	v_lshlrev_b64 v[68:69], 10, v[146:147]
	v_lshl_add_u64 v[72:73], v[156:157], 0, v[68:69]
	v_cvt_pk_bf16_f32 v67, v70, v71
	global_store_dwordx4 v[72:73], v[64:67], off offset:256
	s_and_b64 vcc, exec, s[6:7]
	s_cbranch_vccnz .LBB0_213
	v_add_u32_e32 v64, 16, v144
	v_ashrrev_i32_e32 v64, 6, v64
	v_cndmask_b32_e64 v64, v145, v64, s[10:11]
	v_lshlrev_b32_e32 v64, 4, v64
	v_ashrrev_i32_e32 v65, 31, v64
	v_lshlrev_b64 v[74:75], 2, v[64:65]
	v_lshl_add_u64 v[68:69], v[154:155], 0, v[74:75]
	v_lshl_add_u64 v[78:79], v[152:153], 0, v[74:75]
	global_load_dwordx4 v[64:67], v[68:69], off
	s_nop 0
	global_load_dwordx4 v[68:71], v[68:69], off offset:16
	s_nop 0
	global_load_dwordx4 v[74:77], v[78:79], off
	s_nop 0
	global_load_dwordx4 v[78:81], v[78:79], off offset:16
	v_and_b32_e32 v83, 64, v232
	v_xor_b32_e32 v82, 32, v232
	v_add_u32_e32 v83, 64, v83
	v_cmp_lt_i32_e32 vcc, v82, v83
	s_waitcnt vmcnt(0) lgkmcnt(0)
	v_pk_mul_f32 v[64:65], v[52:53], v[64:65]
	v_cndmask_b32_e32 v82, v232, v82, vcc
	v_lshlrev_b32_e32 v87, 2, v82
	ds_bpermute_b32 v86, v87, v54
	ds_bpermute_b32 v88, v87, v50
	ds_bpermute_b32 v82, v87, v52
	ds_bpermute_b32 v83, v87, v53
	ds_bpermute_b32 v84, v87, v48
	s_waitcnt lgkmcnt(4)
	v_mul_f32_e32 v86, v150, v86
	v_mul_f32_e32 v86, v76, v86
	s_waitcnt lgkmcnt(3)
	v_mul_f32_e32 v76, v150, v88
	v_mul_f32_e32 v88, v80, v76
	ds_bpermute_b32 v76, v87, v55
	ds_bpermute_b32 v80, v87, v51
	ds_bpermute_b32 v85, v87, v49
	s_waitcnt lgkmcnt(4)
	v_pk_mul_f32 v[82:83], v[150:151], v[82:83] op_sel_hi:[0,1]
	v_mov_b32_e32 v90, v67
	s_waitcnt lgkmcnt(2)
	v_mul_f32_e32 v91, v150, v76
	v_mov_b32_e32 v76, v55
	v_pk_fma_f32 v[64:65], v[74:75], v[82:83], v[64:65]
	s_waitcnt lgkmcnt(1)
	v_mul_f32_e32 v75, v150, v80
	v_mov_b32_e32 v80, v51
	v_mov_b32_e32 v74, v71
	v_pk_mul_f32 v[76:77], v[76:77], v[90:91]
	v_pk_mul_f32 v[74:75], v[80:81], v[74:75]
	v_pk_mul_f32 v[68:69], v[48:49], v[68:69]
	s_waitcnt lgkmcnt(0)
	v_pk_mul_f32 v[84:85], v[150:151], v[84:85] op_sel_hi:[0,1]
	v_mul_f32_e32 v66, v54, v66
	v_mul_f32_e32 v70, v50, v70
	v_mov_b32_e32 v67, v76
	v_mov_b32_e32 v87, v77
	v_mov_b32_e32 v71, v74
	v_mov_b32_e32 v89, v75
	v_pk_add_f32 v[66:67], v[66:67], v[86:87]
	v_pk_fma_f32 v[68:69], v[78:79], v[84:85], v[68:69]
	v_pk_add_f32 v[70:71], v[70:71], v[88:89]
	s_branch .LBB0_214

; __device__ __forceinline__ unsigned cvt_pk_bf16(float lo, float hi) { unsigned r; asm volatile("v_cvt_pk_bf16_f32 %0, %1, %2" : "=v"(r) : "v"(lo), "v"(hi)); return r; }
;     __device__ __forceinline__ void operator()(const pg8::f32x4 (&acc)[2][2][4][2], const pg8::Unit& u, int wr, int wc, int fr, int fq) const {
;     ...
;                     const int i0 = 8 * (fq & 1); const bool odd = (wc & 1) != 0; const float sgn = (fq < 2) ? -1.f : 1.f;
; #pragma unroll
;                     for (int ai = 0; ai < 2; ++ai)
; #pragma unroll
;                         for (int m = 0; m < 4; ++m) { const int s = sbase + ai * HALF + m * 16;
;                             f32x4 v0 = acc[ai][bj][m][0], v1 = acc[ai][bj][m][1];
;                             if (!isctx) {
;                                 const int pos = odd ? (s & 63) : (s >> 6);
;                                 const f32x4 c0 = *(const f32x4*)(ropeC + pos * 16 + i0), c1 = *(const f32x4*)(ropeC + pos * 16 + i0 + 4);
;                                 const f32x4 s0 = *(const f32x4*)(ropeS + pos * 16 + i0), s1 = *(const f32x4*)(ropeS + pos * 16 + i0 + 4);
; #pragma unroll
;                                 for (int j = 0; j < 4; ++j) { const float p0 = __shfl_xor(v0[j], 32), p1 = __shfl_xor(v1[j], 32);
;                                     v0[j] = v0[j] * c0[j] + sgn * p0 * s0[j]; v1[j] = v1[j] * c1[j] + sgn * p1 * s1[j]; }
;                             }
;                             if (pn < 2) { v0 = v0 * QSCALE; v1 = v1 * QSCALE; }
;                             u32x4 w; w.x = cvt_pk_bf16(v0[0], v0[1]); w.y = cvt_pk_bf16(v0[2], v0[3]); w.z = cvt_pk_bf16(v1[0], v1[1]); w.w = cvt_pk_bf16(v1[2], v1[3]);
;                             const size_t grow = grow0 + ai * HALF + m * 16;
;                             if (pn < 2) *(u32x4*)(QB + grow * 512 + pn * 256 + bj * HALF + c8) = w; else *(u32x4*)(KB + grow * 128 + c8) = w; asm volatile("" ::: "memory"); }
.LBB0_214:
	s_mov_b64 s[8:9], 0x100
	v_lshl_add_u64 v[72:73], v[72:73], 0, s[8:9]
	v_pk_mul_f32 v[66:67], v[66:67], s[48:49] op_sel_hi:[1,0]
	v_pk_mul_f32 v[64:65], v[64:65], s[48:49] op_sel_hi:[1,0]
	v_pk_mul_f32 v[68:69], v[68:69], s[48:49] op_sel_hi:[1,0]
	v_cvt_pk_bf16_f32 v64, v64, v65
	v_cvt_pk_bf16_f32 v65, v66, v67
	v_pk_mul_f32 v[70:71], v[70:71], s[48:49] op_sel_hi:[1,0]
	v_cvt_pk_bf16_f32 v66, v68, v69
	v_add_co_u32_e32 v68, vcc, 0x4000, v72
	v_cvt_pk_bf16_f32 v67, v70, v71
	s_nop 1
	v_addc_co_u32_e32 v69, vcc, 0, v73, vcc
	global_store_dwordx4 v[68:69], v[64:67], off
	s_and_b64 vcc, exec, s[6:7]
	s_cbranch_vccnz .LBB0_216
	v_add_u32_e32 v64, 32, v144
	v_ashrrev_i32_e32 v64, 6, v64
	v_cndmask_b32_e64 v64, v122, v64, s[10:11]
	v_lshlrev_b32_e32 v64, 4, v64
	v_ashrrev_i32_e32 v65, 31, v64
	v_lshlrev_b64 v[74:75], 2, v[64:65]
	v_lshl_add_u64 v[68:69], v[154:155], 0, v[74:75]
	v_lshl_add_u64 v[78:79], v[152:153], 0, v[74:75]
	global_load_dwordx4 v[64:67], v[68:69], off
	s_nop 0
	global_load_dwordx4 v[68:71], v[68:69], off offset:16
	s_nop 0
	global_load_dwordx4 v[74:77], v[78:79], off
	s_nop 0
	global_load_dwordx4 v[78:81], v[78:79], off offset:16
	v_and_b32_e32 v83, 64, v232
	v_xor_b32_e32 v82, 32, v232
	v_add_u32_e32 v83, 64, v83
	v_cmp_lt_i32_e32 vcc, v82, v83
	s_waitcnt vmcnt(0) lgkmcnt(0)
	v_pk_mul_f32 v[64:65], v[44:45], v[64:65]
	v_cndmask_b32_e32 v82, v232, v82, vcc
	v_lshlrev_b32_e32 v87, 2, v82
	ds_bpermute_b32 v86, v87, v46
	ds_bpermute_b32 v88, v87, v42
	ds_bpermute_b32 v82, v87, v44
	ds_bpermute_b32 v83, v87, v45
	ds_bpermute_b32 v84, v87, v40
	s_waitcnt lgkmcnt(4)
	v_mul_f32_e32 v86, v150, v86
	v_mul_f32_e32 v86, v76, v86
	s_waitcnt lgkmcnt(3)
	v_mul_f32_e32 v76, v150, v88
	v_mul_f32_e32 v88, v80, v76
	ds_bpermute_b32 v76, v87, v47
	ds_bpermute_b32 v80, v87, v43
	ds_bpermute_b32 v85, v87, v41
	s_waitcnt lgkmcnt(4)
	v_pk_mul_f32 v[82:83], v[150:151], v[82:83] op_sel_hi:[0,1]
	v_mov_b32_e32 v90, v67
	s_waitcnt lgkmcnt(2)
	v_mul_f32_e32 v91, v150, v76
	v_mov_b32_e32 v76, v47
	v_pk_fma_f32 v[64:65], v[74:75], v[82:83], v[64:65]
	s_waitcnt lgkmcnt(1)
	v_mul_f32_e32 v75, v150, v80
	v_mov_b32_e32 v80, v43
	v_mov_b32_e32 v74, v71
	v_pk_mul_f32 v[76:77], v[76:77], v[90:91]
	v_pk_mul_f32 v[74:75], v[80:81], v[74:75]
	v_pk_mul_f32 v[68:69], v[40:41], v[68:69]
	s_waitcnt lgkmcnt(0)
	v_pk_mul_f32 v[84:85], v[150:151], v[84:85] op_sel_hi:[0,1]
	v_mul_f32_e32 v66, v46, v66
	v_mul_f32_e32 v70, v42, v70
	v_mov_b32_e32 v67, v76
	v_mov_b32_e32 v87, v77
	v_mov_b32_e32 v71, v74
	v_mov_b32_e32 v89, v75
	v_pk_add_f32 v[66:67], v[66:67], v[86:87]
	v_pk_fma_f32 v[68:69], v[78:79], v[84:85], v[68:69]
	v_pk_add_f32 v[70:71], v[70:71], v[88:89]
	s_branch .LBB0_217

; __device__ __forceinline__ unsigned cvt_pk_bf16(float lo, float hi) { unsigned r; asm volatile("v_cvt_pk_bf16_f32 %0, %1, %2" : "=v"(r) : "v"(lo), "v"(hi)); return r; }
;     __device__ __forceinline__ void operator()(const pg8::f32x4 (&acc)[2][2][4][2], const pg8::Unit& u, int wr, int wc, int fr, int fq) const {
;     ...
;                     const int i0 = 8 * (fq & 1); const bool odd = (wc & 1) != 0; const float sgn = (fq < 2) ? -1.f : 1.f;
; #pragma unroll
;                     for (int ai = 0; ai < 2; ++ai)
; #pragma unroll
;                         for (int m = 0; m < 4; ++m) { const int s = sbase + ai * HALF + m * 16;
;                             f32x4 v0 = acc[ai][bj][m][0], v1 = acc[ai][bj][m][1];
;                             if (!isctx) {
;                                 const int pos = odd ? (s & 63) : (s >> 6);
;                                 const f32x4 c0 = *(const f32x4*)(ropeC + pos * 16 + i0), c1 = *(const f32x4*)(ropeC + pos * 16 + i0 + 4);
;                                 const f32x4 s0 = *(const f32x4*)(ropeS + pos * 16 + i0), s1 = *(const f32x4*)(ropeS + pos * 16 + i0 + 4);
; #pragma unroll
;                                 for (int j = 0; j < 4; ++j) { const float p0 = __shfl_xor(v0[j], 32), p1 = __shfl_xor(v1[j], 32);
;                                     v0[j] = v0[j] * c0[j] + sgn * p0 * s0[j]; v1[j] = v1[j] * c1[j] + sgn * p1 * s1[j]; }
;                             }
;                             if (pn < 2) { v0 = v0 * QSCALE; v1 = v1 * QSCALE; }
;                             u32x4 w; w.x = cvt_pk_bf16(v0[0], v0[1]); w.y = cvt_pk_bf16(v0[2], v0[3]); w.z = cvt_pk_bf16(v1[0], v1[1]); w.w = cvt_pk_bf16(v1[2], v1[3]);
;                             const size_t grow = grow0 + ai * HALF + m * 16;
;                             if (pn < 2) *(u32x4*)(QB + grow * 512 + pn * 256 + bj * HALF + c8) = w; else *(u32x4*)(KB + grow * 128 + c8) = w; asm volatile("" ::: "memory"); }
.LBB0_217:
	v_pk_mul_f32 v[66:67], v[66:67], s[48:49] op_sel_hi:[1,0]
	v_pk_mul_f32 v[64:65], v[64:65], s[48:49] op_sel_hi:[1,0]
	v_pk_mul_f32 v[68:69], v[68:69], s[48:49] op_sel_hi:[1,0]
	v_cvt_pk_bf16_f32 v64, v64, v65
	v_cvt_pk_bf16_f32 v65, v66, v67
	v_pk_mul_f32 v[70:71], v[70:71], s[48:49] op_sel_hi:[1,0]
	v_cvt_pk_bf16_f32 v66, v68, v69
	v_add_co_u32_e32 v68, vcc, 0x8000, v72
	v_cvt_pk_bf16_f32 v67, v70, v71
	s_nop 1
	v_addc_co_u32_e32 v69, vcc, 0, v73, vcc
	global_store_dwordx4 v[68:69], v[64:67], off
	s_and_b64 vcc, exec, s[6:7]
	s_cbranch_vccnz .LBB0_219
	v_add_u32_e32 v64, 48, v144
	v_ashrrev_i32_e32 v64, 6, v64
	v_cndmask_b32_e64 v64, v112, v64, s[10:11]
	v_lshlrev_b32_e32 v64, 4, v64
	v_ashrrev_i32_e32 v65, 31, v64
	v_lshlrev_b64 v[74:75], 2, v[64:65]
	v_lshl_add_u64 v[68:69], v[154:155], 0, v[74:75]
	v_lshl_add_u64 v[78:79], v[152:153], 0, v[74:75]
	global_load_dwordx4 v[64:67], v[68:69], off
	s_nop 0
	global_load_dwordx4 v[68:71], v[68:69], off offset:16
	s_nop 0
	global_load_dwordx4 v[74:77], v[78:79], off
	s_nop 0
	global_load_dwordx4 v[78:81], v[78:79], off offset:16
	v_and_b32_e32 v83, 64, v232
	v_xor_b32_e32 v82, 32, v232
	v_add_u32_e32 v83, 64, v83
	v_cmp_lt_i32_e32 vcc, v82, v83
	s_waitcnt vmcnt(0) lgkmcnt(0)
	v_pk_mul_f32 v[64:65], v[36:37], v[64:65]
	v_cndmask_b32_e32 v82, v232, v82, vcc
	v_lshlrev_b32_e32 v87, 2, v82
	ds_bpermute_b32 v86, v87, v38
	ds_bpermute_b32 v88, v87, v34
	ds_bpermute_b32 v82, v87, v36
	ds_bpermute_b32 v83, v87, v37
	ds_bpermute_b32 v84, v87, v32
	s_waitcnt lgkmcnt(4)
	v_mul_f32_e32 v86, v150, v86
	v_mul_f32_e32 v86, v76, v86
	s_waitcnt lgkmcnt(3)
	v_mul_f32_e32 v76, v150, v88
	v_mul_f32_e32 v88, v80, v76
	ds_bpermute_b32 v76, v87, v39
	ds_bpermute_b32 v80, v87, v35
	ds_bpermute_b32 v85, v87, v33
	s_waitcnt lgkmcnt(4)
	v_pk_mul_f32 v[82:83], v[150:151], v[82:83] op_sel_hi:[0,1]
	v_mov_b32_e32 v90, v67
	s_waitcnt lgkmcnt(2)
	v_mul_f32_e32 v91, v150, v76
	v_mov_b32_e32 v76, v39
	v_pk_fma_f32 v[64:65], v[74:75], v[82:83], v[64:65]
	s_waitcnt lgkmcnt(1)
	v_mul_f32_e32 v75, v150, v80
	v_mov_b32_e32 v80, v35
	v_mov_b32_e32 v74, v71
	v_pk_mul_f32 v[76:77], v[76:77], v[90:91]
	v_pk_mul_f32 v[74:75], v[80:81], v[74:75]
	v_pk_mul_f32 v[68:69], v[32:33], v[68:69]
	s_waitcnt lgkmcnt(0)
	v_pk_mul_f32 v[84:85], v[150:151], v[84:85] op_sel_hi:[0,1]
	v_mul_f32_e32 v66, v38, v66
	v_mul_f32_e32 v70, v34, v70
	v_mov_b32_e32 v67, v76
	v_mov_b32_e32 v87, v77
	v_mov_b32_e32 v71, v74
	v_mov_b32_e32 v89, v75
	v_pk_add_f32 v[66:67], v[66:67], v[86:87]
	v_pk_fma_f32 v[68:69], v[78:79], v[84:85], v[68:69]
	v_pk_add_f32 v[70:71], v[70:71], v[88:89]
	s_branch .LBB0_220

; __device__ __forceinline__ unsigned cvt_pk_bf16(float lo, float hi) { unsigned r; asm volatile("v_cvt_pk_bf16_f32 %0, %1, %2" : "=v"(r) : "v"(lo), "v"(hi)); return r; }
;     __device__ __forceinline__ void operator()(const pg8::f32x4 (&acc)[2][2][4][2], const pg8::Unit& u, int wr, int wc, int fr, int fq) const {
;     ...
;                     const int i0 = 8 * (fq & 1); const bool odd = (wc & 1) != 0; const float sgn = (fq < 2) ? -1.f : 1.f;
; #pragma unroll
;                     for (int ai = 0; ai < 2; ++ai)
; #pragma unroll
;                         for (int m = 0; m < 4; ++m) { const int s = sbase + ai * HALF + m * 16;
;                             f32x4 v0 = acc[ai][bj][m][0], v1 = acc[ai][bj][m][1];
;                             if (!isctx) {
;                                 const int pos = odd ? (s & 63) : (s >> 6);
;                                 const f32x4 c0 = *(const f32x4*)(ropeC + pos * 16 + i0), c1 = *(const f32x4*)(ropeC + pos * 16 + i0 + 4);
;                                 const f32x4 s0 = *(const f32x4*)(ropeS + pos * 16 + i0), s1 = *(const f32x4*)(ropeS + pos * 16 + i0 + 4);
; #pragma unroll
;                                 for (int j = 0; j < 4; ++j) { const float p0 = __shfl_xor(v0[j], 32), p1 = __shfl_xor(v1[j], 32);
;                                     v0[j] = v0[j] * c0[j] + sgn * p0 * s0[j]; v1[j] = v1[j] * c1[j] + sgn * p1 * s1[j]; }
;                             }
;                             if (pn < 2) { v0 = v0 * QSCALE; v1 = v1 * QSCALE; }
;                             u32x4 w; w.x = cvt_pk_bf16(v0[0], v0[1]); w.y = cvt_pk_bf16(v0[2], v0[3]); w.z = cvt_pk_bf16(v1[0], v1[1]); w.w = cvt_pk_bf16(v1[2], v1[3]);
;                             const size_t grow = grow0 + ai * HALF + m * 16;
;                             if (pn < 2) *(u32x4*)(QB + grow * 512 + pn * 256 + bj * HALF + c8) = w; else *(u32x4*)(KB + grow * 128 + c8) = w; asm volatile("" ::: "memory"); }
.LBB0_220:
	v_pk_mul_f32 v[66:67], v[66:67], s[48:49] op_sel_hi:[1,0]
	v_pk_mul_f32 v[64:65], v[64:65], s[48:49] op_sel_hi:[1,0]
	v_pk_mul_f32 v[68:69], v[68:69], s[48:49] op_sel_hi:[1,0]
	v_cvt_pk_bf16_f32 v64, v64, v65
	v_cvt_pk_bf16_f32 v65, v66, v67
	v_pk_mul_f32 v[70:71], v[70:71], s[48:49] op_sel_hi:[1,0]
	v_cvt_pk_bf16_f32 v66, v68, v69
	v_add_co_u32_e32 v68, vcc, 0xc000, v72
	v_cvt_pk_bf16_f32 v67, v70, v71
	s_nop 1
	v_addc_co_u32_e32 v69, vcc, 0, v73, vcc
	global_store_dwordx4 v[68:69], v[64:67], off
	s_and_b64 vcc, exec, s[6:7]
	s_cbranch_vccnz .LBB0_222
	v_add_u32_e32 v64, 0x80, v144
	v_ashrrev_i32_e32 v64, 6, v64
	v_cndmask_b32_e64 v64, v149, v64, s[10:11]
	v_lshlrev_b32_e32 v64, 4, v64
	v_ashrrev_i32_e32 v65, 31, v64
	v_lshlrev_b64 v[74:75], 2, v[64:65]
	v_lshl_add_u64 v[68:69], v[154:155], 0, v[74:75]
	v_lshl_add_u64 v[78:79], v[152:153], 0, v[74:75]
	global_load_dwordx4 v[64:67], v[68:69], off
	s_nop 0
	global_load_dwordx4 v[68:71], v[68:69], off offset:16
	s_nop 0
	global_load_dwordx4 v[74:77], v[78:79], off
	s_nop 0
	global_load_dwordx4 v[78:81], v[78:79], off offset:16
	v_and_b32_e32 v83, 64, v232
	v_xor_b32_e32 v82, 32, v232
	v_add_u32_e32 v83, 64, v83
	v_cmp_lt_i32_e32 vcc, v82, v83
	s_waitcnt vmcnt(0) lgkmcnt(0)
	v_pk_mul_f32 v[64:65], v[28:29], v[64:65]
	v_cndmask_b32_e32 v82, v232, v82, vcc
	v_lshlrev_b32_e32 v87, 2, v82
	ds_bpermute_b32 v86, v87, v30
	ds_bpermute_b32 v88, v87, v26
	ds_bpermute_b32 v82, v87, v28
	ds_bpermute_b32 v83, v87, v29
	ds_bpermute_b32 v84, v87, v24
	s_waitcnt lgkmcnt(4)
	v_mul_f32_e32 v86, v150, v86
	v_mul_f32_e32 v86, v76, v86
	s_waitcnt lgkmcnt(3)
	v_mul_f32_e32 v76, v150, v88
	v_mul_f32_e32 v88, v80, v76
	ds_bpermute_b32 v76, v87, v31
	ds_bpermute_b32 v80, v87, v27
	ds_bpermute_b32 v85, v87, v25
	s_waitcnt lgkmcnt(4)
	v_pk_mul_f32 v[82:83], v[150:151], v[82:83] op_sel_hi:[0,1]
	v_mov_b32_e32 v90, v67
	s_waitcnt lgkmcnt(2)
	v_mul_f32_e32 v91, v150, v76
	v_mov_b32_e32 v76, v31
	v_pk_fma_f32 v[64:65], v[74:75], v[82:83], v[64:65]
	s_waitcnt lgkmcnt(1)
	v_mul_f32_e32 v75, v150, v80
	v_mov_b32_e32 v80, v27
	v_mov_b32_e32 v74, v71
	v_pk_mul_f32 v[76:77], v[76:77], v[90:91]
	v_pk_mul_f32 v[74:75], v[80:81], v[74:75]
	v_pk_mul_f32 v[68:69], v[24:25], v[68:69]
	s_waitcnt lgkmcnt(0)
	v_pk_mul_f32 v[84:85], v[150:151], v[84:85] op_sel_hi:[0,1]
	v_mul_f32_e32 v66, v30, v66
	v_mul_f32_e32 v70, v26, v70
	v_mov_b32_e32 v67, v76
	v_mov_b32_e32 v87, v77
	v_mov_b32_e32 v71, v74
	v_mov_b32_e32 v89, v75
	v_pk_add_f32 v[66:67], v[66:67], v[86:87]
	v_pk_fma_f32 v[68:69], v[78:79], v[84:85], v[68:69]
	v_pk_add_f32 v[70:71], v[70:71], v[88:89]
	s_branch .LBB0_223

; __device__ __forceinline__ unsigned cvt_pk_bf16(float lo, float hi) { unsigned r; asm volatile("v_cvt_pk_bf16_f32 %0, %1, %2" : "=v"(r) : "v"(lo), "v"(hi)); return r; }
;     __device__ __forceinline__ void operator()(const pg8::f32x4 (&acc)[2][2][4][2], const pg8::Unit& u, int wr, int wc, int fr, int fq) const {
;     ...
;                     const int i0 = 8 * (fq & 1); const bool odd = (wc & 1) != 0; const float sgn = (fq < 2) ? -1.f : 1.f;
; #pragma unroll
;                     for (int ai = 0; ai < 2; ++ai)
; #pragma unroll
;                         for (int m = 0; m < 4; ++m) { const int s = sbase + ai * HALF + m * 16;
;                             f32x4 v0 = acc[ai][bj][m][0], v1 = acc[ai][bj][m][1];
;                             if (!isctx) {
;                                 const int pos = odd ? (s & 63) : (s >> 6);
;                                 const f32x4 c0 = *(const f32x4*)(ropeC + pos * 16 + i0), c1 = *(const f32x4*)(ropeC + pos * 16 + i0 + 4);
;                                 const f32x4 s0 = *(const f32x4*)(ropeS + pos * 16 + i0), s1 = *(const f32x4*)(ropeS + pos * 16 + i0 + 4);
; #pragma unroll
;                                 for (int j = 0; j < 4; ++j) { const float p0 = __shfl_xor(v0[j], 32), p1 = __shfl_xor(v1[j], 32);
;                                     v0[j] = v0[j] * c0[j] + sgn * p0 * s0[j]; v1[j] = v1[j] * c1[j] + sgn * p1 * s1[j]; }
;                             }
;                             if (pn < 2) { v0 = v0 * QSCALE; v1 = v1 * QSCALE; }
;                             u32x4 w; w.x = cvt_pk_bf16(v0[0], v0[1]); w.y = cvt_pk_bf16(v0[2], v0[3]); w.z = cvt_pk_bf16(v1[0], v1[1]); w.w = cvt_pk_bf16(v1[2], v1[3]);
;                             const size_t grow = grow0 + ai * HALF + m * 16;
;                             if (pn < 2) *(u32x4*)(QB + grow * 512 + pn * 256 + bj * HALF + c8) = w; else *(u32x4*)(KB + grow * 128 + c8) = w; asm volatile("" ::: "memory"); }
.LBB0_223:
	v_pk_mul_f32 v[66:67], v[66:67], s[48:49] op_sel_hi:[1,0]
	v_pk_mul_f32 v[64:65], v[64:65], s[48:49] op_sel_hi:[1,0]
	v_pk_mul_f32 v[68:69], v[68:69], s[48:49] op_sel_hi:[1,0]
	v_cvt_pk_bf16_f32 v64, v64, v65
	v_cvt_pk_bf16_f32 v65, v66, v67
	v_pk_mul_f32 v[70:71], v[70:71], s[48:49] op_sel_hi:[1,0]
	v_cvt_pk_bf16_f32 v66, v68, v69
	v_add_co_u32_e32 v68, vcc, 0x20000, v72
	v_cvt_pk_bf16_f32 v67, v70, v71
	s_nop 1
	v_addc_co_u32_e32 v69, vcc, 0, v73, vcc
	global_store_dwordx4 v[68:69], v[64:67], off
	s_and_b64 vcc, exec, s[6:7]
	s_cbranch_vccnz .LBB0_225
	v_add_u32_e32 v64, 0x90, v144
	v_ashrrev_i32_e32 v64, 6, v64
	v_cndmask_b32_e64 v64, v145, v64, s[10:11]
	v_lshlrev_b32_e32 v64, 4, v64
	v_ashrrev_i32_e32 v65, 31, v64
	v_lshlrev_b64 v[74:75], 2, v[64:65]
	v_lshl_add_u64 v[68:69], v[154:155], 0, v[74:75]
	v_lshl_add_u64 v[78:79], v[152:153], 0, v[74:75]
	global_load_dwordx4 v[64:67], v[68:69], off
	s_nop 0
	global_load_dwordx4 v[68:71], v[68:69], off offset:16
	s_nop 0
	global_load_dwordx4 v[74:77], v[78:79], off
	s_nop 0
	global_load_dwordx4 v[78:81], v[78:79], off offset:16
	v_and_b32_e32 v83, 64, v232
	v_xor_b32_e32 v82, 32, v232
	v_add_u32_e32 v83, 64, v83
	v_cmp_lt_i32_e32 vcc, v82, v83
	s_waitcnt vmcnt(0) lgkmcnt(0)
	v_pk_mul_f32 v[64:65], v[20:21], v[64:65]
	v_cndmask_b32_e32 v82, v232, v82, vcc
	v_lshlrev_b32_e32 v87, 2, v82
	ds_bpermute_b32 v86, v87, v22
	ds_bpermute_b32 v88, v87, v18
	ds_bpermute_b32 v82, v87, v20
	ds_bpermute_b32 v83, v87, v21
	ds_bpermute_b32 v84, v87, v16
	s_waitcnt lgkmcnt(4)
	v_mul_f32_e32 v86, v150, v86
	v_mul_f32_e32 v86, v76, v86
	s_waitcnt lgkmcnt(3)
	v_mul_f32_e32 v76, v150, v88
	v_mul_f32_e32 v88, v80, v76
	ds_bpermute_b32 v76, v87, v23
	ds_bpermute_b32 v80, v87, v19
	ds_bpermute_b32 v85, v87, v17
	s_waitcnt lgkmcnt(4)
	v_pk_mul_f32 v[82:83], v[150:151], v[82:83] op_sel_hi:[0,1]
	v_mov_b32_e32 v90, v67
	s_waitcnt lgkmcnt(2)
	v_mul_f32_e32 v91, v150, v76
	v_mov_b32_e32 v76, v23
	v_pk_fma_f32 v[64:65], v[74:75], v[82:83], v[64:65]
	s_waitcnt lgkmcnt(1)
	v_mul_f32_e32 v75, v150, v80
	v_mov_b32_e32 v80, v19
	v_mov_b32_e32 v74, v71
	v_pk_mul_f32 v[76:77], v[76:77], v[90:91]
	v_pk_mul_f32 v[74:75], v[80:81], v[74:75]
	v_pk_mul_f32 v[68:69], v[16:17], v[68:69]
	s_waitcnt lgkmcnt(0)
	v_pk_mul_f32 v[84:85], v[150:151], v[84:85] op_sel_hi:[0,1]
	v_mul_f32_e32 v66, v22, v66
	v_mul_f32_e32 v70, v18, v70
	v_mov_b32_e32 v67, v76
	v_mov_b32_e32 v87, v77
	v_mov_b32_e32 v71, v74
	v_mov_b32_e32 v89, v75
	v_pk_add_f32 v[66:67], v[66:67], v[86:87]
	v_pk_fma_f32 v[68:69], v[78:79], v[84:85], v[68:69]
	v_pk_add_f32 v[70:71], v[70:71], v[88:89]
	s_branch .LBB0_226

; __device__ __forceinline__ unsigned cvt_pk_bf16(float lo, float hi) { unsigned r; asm volatile("v_cvt_pk_bf16_f32 %0, %1, %2" : "=v"(r) : "v"(lo), "v"(hi)); return r; }
;     __device__ __forceinline__ void operator()(const pg8::f32x4 (&acc)[2][2][4][2], const pg8::Unit& u, int wr, int wc, int fr, int fq) const {
;     ...
;                     const int i0 = 8 * (fq & 1); const bool odd = (wc & 1) != 0; const float sgn = (fq < 2) ? -1.f : 1.f;
; #pragma unroll
;                     for (int ai = 0; ai < 2; ++ai)
; #pragma unroll
;                         for (int m = 0; m < 4; ++m) { const int s = sbase + ai * HALF + m * 16;
;                             f32x4 v0 = acc[ai][bj][m][0], v1 = acc[ai][bj][m][1];
;                             if (!isctx) {
;                                 const int pos = odd ? (s & 63) : (s >> 6);
;                                 const f32x4 c0 = *(const f32x4*)(ropeC + pos * 16 + i0), c1 = *(const f32x4*)(ropeC + pos * 16 + i0 + 4);
;                                 const f32x4 s0 = *(const f32x4*)(ropeS + pos * 16 + i0), s1 = *(const f32x4*)(ropeS + pos * 16 + i0 + 4);
; #pragma unroll
;                                 for (int j = 0; j < 4; ++j) { const float p0 = __shfl_xor(v0[j], 32), p1 = __shfl_xor(v1[j], 32);
;                                     v0[j] = v0[j] * c0[j] + sgn * p0 * s0[j]; v1[j] = v1[j] * c1[j] + sgn * p1 * s1[j]; }
;                             }
;                             if (pn < 2) { v0 = v0 * QSCALE; v1 = v1 * QSCALE; }
;                             u32x4 w; w.x = cvt_pk_bf16(v0[0], v0[1]); w.y = cvt_pk_bf16(v0[2], v0[3]); w.z = cvt_pk_bf16(v1[0], v1[1]); w.w = cvt_pk_bf16(v1[2], v1[3]);
;                             const size_t grow = grow0 + ai * HALF + m * 16;
;                             if (pn < 2) *(u32x4*)(QB + grow * 512 + pn * 256 + bj * HALF + c8) = w; else *(u32x4*)(KB + grow * 128 + c8) = w; asm volatile("" ::: "memory"); }
.LBB0_226:
	v_pk_mul_f32 v[66:67], v[66:67], s[48:49] op_sel_hi:[1,0]
	v_pk_mul_f32 v[64:65], v[64:65], s[48:49] op_sel_hi:[1,0]
	v_pk_mul_f32 v[68:69], v[68:69], s[48:49] op_sel_hi:[1,0]
	v_cvt_pk_bf16_f32 v64, v64, v65
	v_cvt_pk_bf16_f32 v65, v66, v67
	v_pk_mul_f32 v[70:71], v[70:71], s[48:49] op_sel_hi:[1,0]
	v_cvt_pk_bf16_f32 v66, v68, v69
	v_add_co_u32_e32 v68, vcc, 0x24000, v72
	v_cvt_pk_bf16_f32 v67, v70, v71
	s_nop 1
	v_addc_co_u32_e32 v69, vcc, 0, v73, vcc
	global_store_dwordx4 v[68:69], v[64:67], off
	s_and_b64 vcc, exec, s[6:7]
	s_cbranch_vccnz .LBB0_228
	v_add_u32_e32 v64, 0xa0, v144
	v_ashrrev_i32_e32 v64, 6, v64
	v_cndmask_b32_e64 v64, v122, v64, s[10:11]
	v_lshlrev_b32_e32 v64, 4, v64
	v_ashrrev_i32_e32 v65, 31, v64
	v_lshlrev_b64 v[74:75], 2, v[64:65]
	v_lshl_add_u64 v[68:69], v[154:155], 0, v[74:75]
	v_lshl_add_u64 v[78:79], v[152:153], 0, v[74:75]
	global_load_dwordx4 v[64:67], v[68:69], off
	s_nop 0
	global_load_dwordx4 v[68:71], v[68:69], off offset:16
	s_nop 0
	global_load_dwordx4 v[74:77], v[78:79], off
	s_nop 0
	global_load_dwordx4 v[78:81], v[78:79], off offset:16
	v_and_b32_e32 v83, 64, v232
	v_xor_b32_e32 v82, 32, v232
	v_add_u32_e32 v83, 64, v83
	v_cmp_lt_i32_e32 vcc, v82, v83
	s_waitcnt vmcnt(0) lgkmcnt(0)
	v_pk_mul_f32 v[64:65], v[12:13], v[64:65]
	v_cndmask_b32_e32 v82, v232, v82, vcc
	v_lshlrev_b32_e32 v87, 2, v82
	ds_bpermute_b32 v86, v87, v14
	ds_bpermute_b32 v88, v87, v10
	ds_bpermute_b32 v82, v87, v12
	ds_bpermute_b32 v83, v87, v13
	ds_bpermute_b32 v84, v87, v8
	s_waitcnt lgkmcnt(4)
	v_mul_f32_e32 v86, v150, v86
	v_mul_f32_e32 v86, v76, v86
	s_waitcnt lgkmcnt(3)
	v_mul_f32_e32 v76, v150, v88
	v_mul_f32_e32 v88, v80, v76
	ds_bpermute_b32 v76, v87, v15
	ds_bpermute_b32 v80, v87, v11
	ds_bpermute_b32 v85, v87, v9
	s_waitcnt lgkmcnt(4)
	v_pk_mul_f32 v[82:83], v[150:151], v[82:83] op_sel_hi:[0,1]
	v_mov_b32_e32 v90, v67
	s_waitcnt lgkmcnt(2)
	v_mul_f32_e32 v91, v150, v76
	v_mov_b32_e32 v76, v15
	v_pk_fma_f32 v[64:65], v[74:75], v[82:83], v[64:65]
	s_waitcnt lgkmcnt(1)
	v_mul_f32_e32 v75, v150, v80
	v_mov_b32_e32 v80, v11
	v_mov_b32_e32 v74, v71
	v_pk_mul_f32 v[76:77], v[76:77], v[90:91]
	v_pk_mul_f32 v[74:75], v[80:81], v[74:75]
	v_pk_mul_f32 v[68:69], v[8:9], v[68:69]
	s_waitcnt lgkmcnt(0)
	v_pk_mul_f32 v[84:85], v[150:151], v[84:85] op_sel_hi:[0,1]
	v_mul_f32_e32 v66, v14, v66
	v_mul_f32_e32 v70, v10, v70
	v_mov_b32_e32 v67, v76
	v_mov_b32_e32 v87, v77
	v_mov_b32_e32 v71, v74
	v_mov_b32_e32 v89, v75
	v_pk_add_f32 v[66:67], v[66:67], v[86:87]
	v_pk_fma_f32 v[68:69], v[78:79], v[84:85], v[68:69]
	v_pk_add_f32 v[70:71], v[70:71], v[88:89]
	s_branch .LBB0_229

; __device__ __forceinline__ unsigned cvt_pk_bf16(float lo, float hi) { unsigned r; asm volatile("v_cvt_pk_bf16_f32 %0, %1, %2" : "=v"(r) : "v"(lo), "v"(hi)); return r; }
;     __device__ __forceinline__ void operator()(const pg8::f32x4 (&acc)[2][2][4][2], const pg8::Unit& u, int wr, int wc, int fr, int fq) const {
;     ...
;                     const int i0 = 8 * (fq & 1); const bool odd = (wc & 1) != 0; const float sgn = (fq < 2) ? -1.f : 1.f;
; #pragma unroll
;                     for (int ai = 0; ai < 2; ++ai)
; #pragma unroll
;                         for (int m = 0; m < 4; ++m) { const int s = sbase + ai * HALF + m * 16;
;                             f32x4 v0 = acc[ai][bj][m][0], v1 = acc[ai][bj][m][1];
;                             if (!isctx) {
;                                 const int pos = odd ? (s & 63) : (s >> 6);
;                                 const f32x4 c0 = *(const f32x4*)(ropeC + pos * 16 + i0), c1 = *(const f32x4*)(ropeC + pos * 16 + i0 + 4);
;                                 const f32x4 s0 = *(const f32x4*)(ropeS + pos * 16 + i0), s1 = *(const f32x4*)(ropeS + pos * 16 + i0 + 4);
; #pragma unroll
;                                 for (int j = 0; j < 4; ++j) { const float p0 = __shfl_xor(v0[j], 32), p1 = __shfl_xor(v1[j], 32);
;                                     v0[j] = v0[j] * c0[j] + sgn * p0 * s0[j]; v1[j] = v1[j] * c1[j] + sgn * p1 * s1[j]; }
;                             }
;                             if (pn < 2) { v0 = v0 * QSCALE; v1 = v1 * QSCALE; }
;                             u32x4 w; w.x = cvt_pk_bf16(v0[0], v0[1]); w.y = cvt_pk_bf16(v0[2], v0[3]); w.z = cvt_pk_bf16(v1[0], v1[1]); w.w = cvt_pk_bf16(v1[2], v1[3]);
;                             const size_t grow = grow0 + ai * HALF + m * 16;
;                             if (pn < 2) *(u32x4*)(QB + grow * 512 + pn * 256 + bj * HALF + c8) = w; else *(u32x4*)(KB + grow * 128 + c8) = w; asm volatile("" ::: "memory"); }
.LBB0_229:
	v_pk_mul_f32 v[66:67], v[66:67], s[48:49] op_sel_hi:[1,0]
	v_pk_mul_f32 v[64:65], v[64:65], s[48:49] op_sel_hi:[1,0]
	v_pk_mul_f32 v[68:69], v[68:69], s[48:49] op_sel_hi:[1,0]
	v_cvt_pk_bf16_f32 v64, v64, v65
	v_cvt_pk_bf16_f32 v65, v66, v67
	v_pk_mul_f32 v[70:71], v[70:71], s[48:49] op_sel_hi:[1,0]
	v_cvt_pk_bf16_f32 v66, v68, v69
	v_add_co_u32_e32 v68, vcc, 0x28000, v72
	v_cvt_pk_bf16_f32 v67, v70, v71
	s_nop 1
	v_addc_co_u32_e32 v69, vcc, 0, v73, vcc
	global_store_dwordx4 v[68:69], v[64:67], off
	s_and_b64 vcc, exec, s[6:7]
	s_cbranch_vccnz .LBB0_231
	v_add_u32_e32 v64, 0xb0, v144
	v_ashrrev_i32_e32 v64, 6, v64
	v_cndmask_b32_e64 v64, v112, v64, s[10:11]
	v_lshlrev_b32_e32 v64, 4, v64
	v_ashrrev_i32_e32 v65, 31, v64
	v_lshlrev_b64 v[74:75], 2, v[64:65]
	v_lshl_add_u64 v[68:69], v[154:155], 0, v[74:75]
	v_lshl_add_u64 v[78:79], v[152:153], 0, v[74:75]
	global_load_dwordx4 v[64:67], v[68:69], off
	s_nop 0
	global_load_dwordx4 v[68:71], v[68:69], off offset:16
	s_nop 0
	global_load_dwordx4 v[74:77], v[78:79], off
	s_nop 0
	global_load_dwordx4 v[78:81], v[78:79], off offset:16
	v_and_b32_e32 v83, 64, v232
	v_xor_b32_e32 v82, 32, v232
	v_add_u32_e32 v83, 64, v83
	v_cmp_lt_i32_e32 vcc, v82, v83
	s_waitcnt vmcnt(0) lgkmcnt(0)
	v_pk_mul_f32 v[64:65], v[4:5], v[64:65]
	v_cndmask_b32_e32 v82, v232, v82, vcc
	v_lshlrev_b32_e32 v87, 2, v82
	ds_bpermute_b32 v86, v87, v6
	ds_bpermute_b32 v88, v87, v2
	ds_bpermute_b32 v82, v87, v4
	ds_bpermute_b32 v83, v87, v5
	ds_bpermute_b32 v84, v87, v0
	s_waitcnt lgkmcnt(4)
	v_mul_f32_e32 v86, v150, v86
	v_mul_f32_e32 v86, v76, v86
	s_waitcnt lgkmcnt(3)
	v_mul_f32_e32 v76, v150, v88
	v_mul_f32_e32 v88, v80, v76
	ds_bpermute_b32 v76, v87, v7
	ds_bpermute_b32 v80, v87, v3
	ds_bpermute_b32 v85, v87, v1
	s_waitcnt lgkmcnt(4)
	v_pk_mul_f32 v[82:83], v[150:151], v[82:83] op_sel_hi:[0,1]
	v_mov_b32_e32 v90, v67
	s_waitcnt lgkmcnt(2)
	v_mul_f32_e32 v91, v150, v76
	v_mov_b32_e32 v76, v7
	v_pk_fma_f32 v[64:65], v[74:75], v[82:83], v[64:65]
	s_waitcnt lgkmcnt(1)
	v_mul_f32_e32 v75, v150, v80
	v_mov_b32_e32 v80, v3
	v_mov_b32_e32 v74, v71
	v_pk_mul_f32 v[76:77], v[76:77], v[90:91]
	v_pk_mul_f32 v[74:75], v[80:81], v[74:75]
	v_pk_mul_f32 v[68:69], v[0:1], v[68:69]
	s_waitcnt lgkmcnt(0)
	v_pk_mul_f32 v[84:85], v[150:151], v[84:85] op_sel_hi:[0,1]
	v_mul_f32_e32 v66, v6, v66
	v_mul_f32_e32 v70, v2, v70
	v_mov_b32_e32 v67, v76
	v_mov_b32_e32 v87, v77
	v_mov_b32_e32 v71, v74
	v_mov_b32_e32 v89, v75
	v_pk_add_f32 v[66:67], v[66:67], v[86:87]
	v_pk_fma_f32 v[68:69], v[78:79], v[84:85], v[68:69]
	v_pk_add_f32 v[70:71], v[70:71], v[88:89]
	s_branch .LBB0_232
